# instruction-selection trims: dilated staging no longer zero-masks clamped rows (their scores underflow via the far position), mul_lo replaced by shifts, scale constant in SGPR; MLA rescale branch take
# speedup vs baseline: 1.0078x; 1.0025x over previous
; DI int v_st64(int k, int c) { const int kk = (k & ~0xC) | ((k & 4) << 1) | ((k & 8) >> 1); return ((kk >> 3) * 2 + (c >> 5)) * 512 + ((kk & 7) * 32 + (c & 31)) * 2; }
; DI void unit(const bf16* __restrict__ QKV, const int* __restrict__ pos, bf16* __restrict__ OA, float* __restrict__ LSE,
;              int b, int h, int d, int r, int qb, float slope, char* lds) {
;     ...
;     for (int i = 0; i < 3; ++i) { const int idx = tid + (i0 + i) * 512, row = idx >> 3, ch = idx & 7, v = u0 - 64 + row; const bool ok = (v >= 0) && (v < L);
;       const unsigned go = (unsigned)((r + d * (ok ? v : 0)) * 64 + ch * 8) * 2u;
;       kreg[i] = *(const bf16x8*)((const char*)base + PLANE + go); vreg[i] = *(const bf16x8*)((const char*)base + 2 * PLANE + go);
;       if (!ok) { kreg[i] = bf16x8{}; vreg[i] = bf16x8{}; } }
; #pragma unroll
;     for (int i = 0; i < 3; ++i) { const int idx = tid + (i0 + i) * 512, row = idx >> 3, ch = idx & 7;
;       *(bf16x8*)(K_lds + PSWZ(row, ch * 16)) = kreg[i]; *(bf16x8*)(V_lds + v_st64(row, ch * 8)) = vreg[i]; }
;     ...
;       for (int j = 0; j < 4; ++j) { const int rr = 4 * g + j, kr = j + 8 * g + 4 * hi;
;         float sc = fmaf(__builtin_fabsf(pqf - pk4[j]), -sl2, p[ta][rr] * C);
;         if (ta == 0) sc = (kr >= r32) ? sc : -1e30f;
;         if (ta == 4) sc = (kr <= r32) ? sc : -1e30f;
.Ldil_noprio:
	s_cmpk_gt_i32 s33, 0xbff
	s_cbranch_scc1 .Ldil_done
	s_add_u32 s0, s26, 0x9c00000
	s_addc_u32 s1, s27, 0
	s_add_u32 s10, s26, 0xfc00000
	s_addc_u32 s11, s27, 0
	s_add_u32 s13, s26, 0x7400000
	s_addc_u32 s38, s27, 0
	s_mov_b32 s9, 0
	s_load_dwordx2 s[40:41], s[98:99], 0x10
	s_movk_i32 s39, 0x70
	s_movk_i32 s42, 0x180
	v_mov_b32_e32 v93, 0
	s_mov_b32 s43, 0x42fc0000
	s_movk_i32 s44, 0x60
	s_mov_b32 s45, 0xf149f2ca
	v_mov_b32_e32 v96, 0x42800000
	s_add_i32 s46, 0, 0x18000
	v_mov_b32_e32 v97, 0xf149f2ca
	v_lshrrev_b32_e32 v234, 3, v242
	v_lshlrev_b32_e32 v235, 4, v242
	v_and_b32_e32 v235, 0x70, v235
	v_lshrrev_b32_e32 v222, 1, v234
	v_and_b32_e32 v222, 7, v222
	v_lshlrev_b32_e32 v222, 4, v222
	v_xor_b32_e32 v222, v222, v235
	v_lshl_or_b32 v222, v234, 7, v222
	v_and_b32_e32 v223, 51, v234
	v_and_b32_e32 v224, 4, v234
	v_lshlrev_b32_e32 v224, 1, v224
	v_or_b32_e32 v223, v223, v224
	v_and_b32_e32 v224, 8, v234
	v_lshrrev_b32_e32 v224, 1, v224
	v_or_b32_e32 v223, v223, v224
	v_lshrrev_b32_e32 v224, 3, v223
	v_lshlrev_b32_e32 v224, 1, v224
	v_bfe_u32 v225, v242, 2, 1
	v_add_u32_e32 v224, v224, v225
	v_lshlrev_b32_e32 v224, 9, v224
	v_and_b32_e32 v225, 7, v223
	v_lshlrev_b32_e32 v225, 5, v225
	v_and_b32_e32 v226, 3, v242
	v_lshl_or_b32 v225, v226, 3, v225
	v_lshlrev_b32_e32 v225, 1, v225
	v_add_u32_e32 v223, v224, v225
	v_add_u32_e32 v223, 0xc000, v223
	v_and_b32_e32 v236, 31, v242
	v_bfe_u32 v237, v242, 5, 1
	v_lshlrev_b32_e32 v237, 2, v237
	v_mov_b32_e32 v238, 0xf149f2ca
	v_mov_b32_e32 v240, 0
	v_add_u32_e32 v239, 0, v237
	v_cmp_ge_u32_e32 vcc, v239, v236
	s_nop 1
	v_cndmask_b32_e32 v134, v238, v240, vcc
	v_add_u32_e32 v239, 1, v237
	v_cmp_ge_u32_e32 vcc, v239, v236
	s_nop 1
	v_cndmask_b32_e32 v135, v238, v240, vcc
	v_add_u32_e32 v239, 2, v237
	v_cmp_ge_u32_e32 vcc, v239, v236
	s_nop 1
	v_cndmask_b32_e32 v136, v238, v240, vcc
	v_add_u32_e32 v239, 3, v237
	v_cmp_ge_u32_e32 vcc, v239, v236
	s_nop 1
	v_cndmask_b32_e32 v137, v238, v240, vcc
	v_add_u32_e32 v239, 8, v237
	v_cmp_ge_u32_e32 vcc, v239, v236
	s_nop 1
	v_cndmask_b32_e32 v138, v238, v240, vcc
	v_add_u32_e32 v239, 9, v237
	v_cmp_ge_u32_e32 vcc, v239, v236
	s_nop 1
	v_cndmask_b32_e32 v139, v238, v240, vcc
	v_add_u32_e32 v239, 10, v237
	v_cmp_ge_u32_e32 vcc, v239, v236
	s_nop 1
	v_cndmask_b32_e32 v140, v238, v240, vcc
	v_add_u32_e32 v239, 11, v237
	v_cmp_ge_u32_e32 vcc, v239, v236
	s_nop 1
	v_cndmask_b32_e32 v141, v238, v240, vcc
	v_add_u32_e32 v239, 16, v237
	v_cmp_ge_u32_e32 vcc, v239, v236
	s_nop 1
	v_cndmask_b32_e32 v142, v238, v240, vcc
	v_add_u32_e32 v239, 17, v237
	v_cmp_ge_u32_e32 vcc, v239, v236
	s_nop 1
	v_cndmask_b32_e32 v143, v238, v240, vcc
	v_add_u32_e32 v239, 18, v237
	v_cmp_ge_u32_e32 vcc, v239, v236
	s_nop 1
	v_cndmask_b32_e32 v144, v238, v240, vcc
	v_add_u32_e32 v239, 19, v237
	v_cmp_ge_u32_e32 vcc, v239, v236
	s_nop 1
	v_cndmask_b32_e32 v145, v238, v240, vcc
	v_add_u32_e32 v239, 24, v237
	v_cmp_ge_u32_e32 vcc, v239, v236
	s_nop 1
	v_cndmask_b32_e32 v148, v238, v240, vcc
	v_add_u32_e32 v239, 25, v237
	v_cmp_ge_u32_e32 vcc, v239, v236
	s_nop 1
	v_cndmask_b32_e32 v149, v238, v240, vcc
	v_add_u32_e32 v239, 26, v237
	v_cmp_ge_u32_e32 vcc, v239, v236
	s_nop 1
	v_cndmask_b32_e32 v150, v238, v240, vcc
	v_add_u32_e32 v239, 27, v237
	v_cmp_ge_u32_e32 vcc, v239, v236
	s_nop 1
	v_cndmask_b32_e32 v152, v238, v240, vcc
	v_add_u32_e32 v239, 0, v237
	v_cmp_le_u32_e32 vcc, v239, v236
	s_nop 1
	v_cndmask_b32_e32 v153, v238, v240, vcc
	v_add_u32_e32 v239, 1, v237
	v_cmp_le_u32_e32 vcc, v239, v236
	s_nop 1
	v_cndmask_b32_e32 v154, v238, v240, vcc
	v_add_u32_e32 v239, 2, v237
	v_cmp_le_u32_e32 vcc, v239, v236
	s_nop 1
	v_cndmask_b32_e32 v155, v238, v240, vcc
	v_add_u32_e32 v239, 3, v237
	v_cmp_le_u32_e32 vcc, v239, v236
	s_nop 1
	v_cndmask_b32_e32 v156, v238, v240, vcc
	v_add_u32_e32 v239, 8, v237
	v_cmp_le_u32_e32 vcc, v239, v236
	s_nop 1
	v_cndmask_b32_e32 v157, v238, v240, vcc
	v_add_u32_e32 v239, 9, v237
	v_cmp_le_u32_e32 vcc, v239, v236
	s_nop 1
	v_cndmask_b32_e32 v158, v238, v240, vcc
	v_add_u32_e32 v239, 10, v237
	v_cmp_le_u32_e32 vcc, v239, v236
	s_nop 1
	v_cndmask_b32_e32 v159, v238, v240, vcc
	v_add_u32_e32 v239, 11, v237
	v_cmp_le_u32_e32 vcc, v239, v236
	s_nop 1
	v_cndmask_b32_e32 v162, v238, v240, vcc
	v_add_u32_e32 v239, 16, v237
	v_cmp_le_u32_e32 vcc, v239, v236
	s_nop 1
	v_cndmask_b32_e32 v163, v238, v240, vcc
	v_add_u32_e32 v239, 17, v237
	v_cmp_le_u32_e32 vcc, v239, v236
	s_nop 1
	v_cndmask_b32_e32 v227, v238, v240, vcc
	v_add_u32_e32 v239, 18, v237
	v_cmp_le_u32_e32 vcc, v239, v236
	s_nop 1
	v_cndmask_b32_e32 v228, v238, v240, vcc
	v_add_u32_e32 v239, 19, v237
	v_cmp_le_u32_e32 vcc, v239, v236
	s_nop 1
	v_cndmask_b32_e32 v229, v238, v240, vcc
	v_add_u32_e32 v239, 24, v237
	v_cmp_le_u32_e32 vcc, v239, v236
	s_nop 1
	v_cndmask_b32_e32 v230, v238, v240, vcc
	v_add_u32_e32 v239, 25, v237
	v_cmp_le_u32_e32 vcc, v239, v236
	s_nop 1
	v_cndmask_b32_e32 v231, v238, v240, vcc
	v_add_u32_e32 v239, 26, v237
	v_cmp_le_u32_e32 vcc, v239, v236
	s_nop 1
	v_cndmask_b32_e32 v232, v238, v240, vcc
	v_add_u32_e32 v239, 27, v237
	v_cmp_le_u32_e32 vcc, v239, v236
	s_nop 1
	v_cndmask_b32_e32 v233, v238, v240, vcc
	s_waitcnt lgkmcnt(0)
	s_mov_b32 s76, 0x3e38aa3b
	s_mov_b32 s47, s33
	s_branch .LBB0_858

; #define SBAR() __builtin_amdgcn_sched_barrier(0)
; DI int v_st64(int k, int c) { const int kk = (k & ~0xC) | ((k & 4) << 1) | ((k & 8) >> 1); return ((kk >> 3) * 2 + (c >> 5)) * 512 + ((kk & 7) * 32 + (c & 31)) * 2; }
; DI void unit(const bf16* __restrict__ QKV, const int* __restrict__ pos, bf16* __restrict__ OA, float* __restrict__ LSE,
;              int b, int h, int d, int r, int qb, float slope, char* lds) {
;     ...
;   auto stage = [&](const int i0) {
;     bf16x8 kreg[3], vreg[3];
; #pragma unroll
;     for (int i = 0; i < 3; ++i) { const int idx = tid + (i0 + i) * 512, row = idx >> 3, ch = idx & 7, v = u0 - 64 + row; const bool ok = (v >= 0) && (v < L);
;       const unsigned go = (unsigned)((r + d * (ok ? v : 0)) * 64 + ch * 8) * 2u;
;       kreg[i] = *(const bf16x8*)((const char*)base + PLANE + go); vreg[i] = *(const bf16x8*)((const char*)base + 2 * PLANE + go);
;       if (!ok) { kreg[i] = bf16x8{}; vreg[i] = bf16x8{}; } }
; #pragma unroll
;     for (int i = 0; i < 3; ++i) { const int idx = tid + (i0 + i) * 512, row = idx >> 3, ch = idx & 7;
;       *(bf16x8*)(K_lds + PSWZ(row, ch * 16)) = kreg[i]; *(bf16x8*)(V_lds + v_st64(row, ch * 8)) = vreg[i]; }
;   };
;   stage(0); SBAR(); stage(3); SBAR();
;   float pkv = 3.0e8f; if (tid < 384) { const int v = u0 - 64 + tid; if (v >= 0 && v < L) pkv = (float)pos[b * SEQ + r + d * v]; }
;   const int uq = u0 + wid * 32 + r32, tq = r + d * uq;
;   bf16x8 qr[4];
; #pragma unroll
;   for (int d0 = 0; d0 < 4; ++d0) qr[d0] = *(const bf16x8*)((const char*)base + (unsigned)(tq * 64 + d0 * 16 + hi * 8) * 2u);
;   const int pq = pos[b * SEQ + tq];
;   if (tid < 384) ((float*)posk)[tid] = pkv;
;   __syncthreads();
.LBB0_864:
	s_and_b32 s48, s47, 7
	s_bfe_u32 s30, s47, 0x30007
	s_ff1_i32_b32 s3, s8
	s_lshr_b32 s49, 0x1000, s3
	s_mov_b32 s77, s3
	s_lshl_b32 s31, s2, 8
	s_lshl_b32 s2, s48, 19
	s_lshl_b32 s3, s30, 22
	s_or_b32 s2, s3, s2
	s_add_u32 s16, s10, s2
	v_mov_b32_e32 v4, v242
	s_addc_u32 s17, s11, 0
	s_sub_i32 s50, s31, 64
	s_add_u32 s18, s16, 0x2000000
	s_addc_u32 s19, s17, 0
	s_add_u32 s20, s16, 0x4000000
	s_addc_u32 s21, s17, 0
	s_lshl_b32 s94, s30, 12
	s_or_b32 s94, s15, s94
	v_ashrrev_i32_e32 v6, 6, v4
	v_lshlrev_b32_e32 v102, 5, v6
	v_and_b32_e32 v100, 31, v4
	v_add_u32_e32 v0, s31, v102
	v_or_b32_e32 v0, v0, v100
	v_bfe_u32 v101, v4, 5, 1
	v_lshlrev_b32_e32 v0, s77, v0
	v_add_u32_e32 v7, s15, v0
	v_lshlrev_b32_e32 v92, 4, v101
	v_lshl_or_b32 v8, v7, 7, v92
	v_lshl_add_u32 v94, s30, 12, v7
	global_load_dwordx4 v[0:3], v8, s[16:17]
	global_load_dwordx4 v[88:91], v8, s[16:17] offset:32
	global_load_dwordx4 v[84:87], v8, s[16:17] offset:64
	global_load_dwordx4 v[80:83], v8, s[16:17] offset:96
	v_ashrrev_i32_e32 v95, 31, v94
	v_lshl_add_u64 v[8:9], v[94:95], 2, s[40:41]
	global_load_dword v103, v[8:9], off
	v_add_u32_e32 v214, s50, v234
	s_add_i32 s95, s50, 64
	v_add_u32_e32 v215, s95, v234
	s_add_i32 s95, s50, 128
	v_add_u32_e32 v216, s95, v234
	s_add_i32 s95, s50, 192
	v_add_u32_e32 v217, s95, v234
	s_add_i32 s95, s50, 256
	v_add_u32_e32 v218, s95, v234
	s_add_i32 s95, s50, 320
	v_add_u32_e32 v219, s95, v234
	v_add_u32_e32 v220, s50, v4
	v_cmp_gt_u32_e64 s[80:81], s49, v214
	v_cmp_gt_u32_e64 s[82:83], s49, v215
	v_cmp_gt_u32_e64 s[84:85], s49, v216
	v_cmp_gt_u32_e64 s[86:87], s49, v217
	v_cmp_gt_u32_e64 s[88:89], s49, v218
	v_cmp_gt_u32_e64 s[90:91], s49, v219
	v_cmp_gt_u32_e64 s[92:93], s49, v220
	v_cmp_gt_i32_e32 vcc, s42, v4
	v_cndmask_b32_e64 v214, 0, v214, s[80:81]
	v_cndmask_b32_e64 v215, 0, v215, s[82:83]
	v_cndmask_b32_e64 v216, 0, v216, s[84:85]
	v_cndmask_b32_e64 v217, 0, v217, s[86:87]
	v_cndmask_b32_e64 v218, 0, v218, s[88:89]
	v_cndmask_b32_e64 v219, 0, v219, s[90:91]
	s_and_b64 s[92:93], s[92:93], vcc
	v_lshlrev_b32_e32 v214, s77, v214
	v_lshlrev_b32_e32 v215, s77, v215
	v_lshlrev_b32_e32 v216, s77, v216
	v_lshlrev_b32_e32 v217, s77, v217
	v_lshlrev_b32_e32 v218, s77, v218
	v_lshlrev_b32_e32 v219, s77, v219
	v_cndmask_b32_e64 v220, 0, v220, s[92:93]
	v_add_u32_e32 v214, s15, v214
	v_add_u32_e32 v215, s15, v215
	v_add_u32_e32 v216, s15, v216
	v_add_u32_e32 v217, s15, v217
	v_add_u32_e32 v218, s15, v218
	v_add_u32_e32 v219, s15, v219
	v_lshlrev_b32_e32 v220, s77, v220
	v_lshl_or_b32 v214, v214, 7, v235
	v_lshl_or_b32 v215, v215, 7, v235
	v_lshl_or_b32 v216, v216, 7, v235
	v_lshl_or_b32 v217, v217, 7, v235
	v_lshl_or_b32 v218, v218, 7, v235
	v_lshl_or_b32 v219, v219, 7, v235
	v_add_lshl_u32 v220, v220, s94, 2
	global_load_dwordx4 v[164:167], v214, s[18:19]
	global_load_dwordx4 v[168:171], v214, s[20:21]
	global_load_dwordx4 v[172:175], v215, s[18:19]
	global_load_dwordx4 v[176:179], v215, s[20:21]
	global_load_dwordx4 v[180:183], v216, s[18:19]
	global_load_dwordx4 v[184:187], v216, s[20:21]
	global_load_dwordx4 v[188:191], v217, s[18:19]
	global_load_dwordx4 v[192:195], v217, s[20:21]
	global_load_dwordx4 v[196:199], v218, s[18:19]
	global_load_dwordx4 v[200:203], v218, s[20:21]
	global_load_dwordx4 v[204:207], v219, s[18:19]
	global_load_dwordx4 v[208:211], v219, s[20:21]
	global_load_dword v213, v220, s[40:41]
	s_waitcnt vmcnt(11)
	ds_write_b128 v222, v[164:167]
	ds_write_b128 v223, v[168:171]
	s_waitcnt vmcnt(9)
	ds_write_b128 v222, v[172:175] offset:8192
	ds_write_b128 v223, v[176:179] offset:8192
	s_waitcnt vmcnt(7)
	ds_write_b128 v222, v[180:183] offset:16384
	ds_write_b128 v223, v[184:187] offset:16384
	s_waitcnt vmcnt(5)
	ds_write_b128 v222, v[188:191] offset:24576
	ds_write_b128 v223, v[192:195] offset:24576
	s_waitcnt vmcnt(3)
	ds_write_b128 v222, v[196:199] offset:32768
	ds_write_b128 v223, v[200:203] offset:32768
	s_waitcnt vmcnt(1)
	ds_write_b128 v222, v[204:207] offset:40960
	ds_write_b128 v223, v[208:211] offset:40960
	s_waitcnt vmcnt(0)
	v_cmp_gt_i32_e32 vcc, s42, v4
	v_cvt_f32_i32_e32 v213, v213
	v_mov_b32_e32 v5, 0x4d8f0d18
	v_cndmask_b32_e64 v5, v5, v213, s[92:93]
	s_and_saveexec_b64 s[2:3], vcc
	v_lshl_add_u32 v7, v4, 2, 0
	v_add_u32_e32 v7, 0x18000, v7
	ds_write_b32 v7, v5
	s_or_b64 exec, exec, s[2:3]
	v_lshlrev_b32_e32 v5, 3, v4
	v_lshlrev_b32_e32 v99, 12, v6
	v_bitop3_b32 v7, v92, v5, s39 bitop3:0x78
	v_lshl_or_b32 v14, v100, 7, v99
	v_add3_u32 v15, 0, v7, v14
	s_waitcnt lgkmcnt(0)
	s_barrier
; #define SBAR() __builtin_amdgcn_sched_barrier(0)
; DI void unit(const bf16* __restrict__ QKV, const int* __restrict__ pos, bf16* __restrict__ OA, float* __restrict__ LSE,
;              int b, int h, int d, int r, int qb, float slope, char* lds) {
;     ...
;   f32x16 p[5];
; #pragma unroll
;   for (int ta = 0; ta < 5; ++ta) { p[ta] = f32x16{};
; #pragma unroll
;     for (int d0 = 0; d0 < 4; ++d0) { const bf16x8 a = *(const bf16x8*)(K_lds + PSWZ(wid * 32 + ta * 32 + r32, (d0 * 16 + hi * 8) * 2));
;       p[ta] = __builtin_amdgcn_mfma_f32_32x32x16_bf16(a, qr[d0], p[ta], 0, 0, 0); }
;     SBAR(); }
;   const float C = 0.125f * 1.4426950408889634f, sl2 = slope * 1.4426950408889634f;
;   const float* pbase = (const float*)posk + wid * 32 + 4 * hi; const float pqf = (float)pq;
;   float mx = -1e30f;
; #pragma unroll
;   for (int ta = 0; ta < 5; ++ta) {
; #pragma unroll
;     for (int g = 0; g < 4; ++g) { const f32x4 pk4 = *(const f32x4*)(pbase + ta * 32 + 8 * g);
; #pragma unroll
;       for (int j = 0; j < 4; ++j) { const int rr = 4 * g + j, kr = j + 8 * g + 4 * hi;
;         float sc = fmaf(__builtin_fabsf(pqf - pk4[j]), -sl2, p[ta][rr] * C);
;         if (ta == 0) sc = (kr >= r32) ? sc : -1e30f;
;         if (ta == 4) sc = (kr <= r32) ? sc : -1e30f;
;         p[ta][rr] = sc; mx = fmaxf(mx, sc); } }
	ds_read_b128 v[6:9], v15
	v_and_b32_e32 v5, 0x70, v5
	v_bitop3_b32 v10, v92, v5, 32 bitop3:0x36
	v_add3_u32 v104, 0, v10, v14
	ds_read_b128 v[10:13], v104
	s_waitcnt vmcnt(4) lgkmcnt(1)
	v_mfma_f32_32x32x16_bf16 v[64:79], v[6:9], v[0:3], 0
	v_bitop3_b32 v6, v92, v5, 64 bitop3:0x36
	v_add3_u32 v108, 0, v6, v14
	ds_read_b128 v[6:9], v108
	v_bitop3_b32 v5, v92, v5, s44 bitop3:0x36
	v_add3_u32 v109, 0, v5, v14
	s_add_i32 s2, s48, 1
	v_cvt_f32_ubyte0_e32 v16, s2
	s_waitcnt vmcnt(3) lgkmcnt(1)
	v_mfma_f32_32x32x16_bf16 v[64:79], v[10:13], v[88:91], v[64:79]
	ds_read_b128 v[10:13], v109
	v_cmp_lt_f32_e32 vcc, s43, v16
	s_and_b64 s[2:3], vcc, exec
	s_cselect_b32 s2, 0xffffffc0, 0
	v_cndmask_b32_e32 v17, 0, v96, vcc
	v_sub_f32_e32 v5, v17, v16
	v_exp_f32_e32 v5, v5
	s_waitcnt vmcnt(2) lgkmcnt(1)
	v_mfma_f32_32x32x16_bf16 v[64:79], v[6:9], v[84:87], v[64:79]
	s_ashr_i32 s15, s14, 31
	v_and_b32_e32 v98, 63, v4
	v_ldexp_f32 v110, v5, s2
	s_waitcnt vmcnt(1) lgkmcnt(0)
	v_mfma_f32_32x32x16_bf16 v[64:79], v[10:13], v[80:83], v[64:79]
	ds_read_b128 v[4:7], v15 offset:4096
	ds_read_b128 v[8:11], v104 offset:4096
	s_waitcnt lgkmcnt(1)
	v_mfma_f32_32x32x16_bf16 v[48:63], v[4:7], v[0:3], 0
	s_waitcnt lgkmcnt(0)
	v_mfma_f32_32x32x16_bf16 v[48:63], v[8:11], v[88:91], v[48:63]
	ds_read_b128 v[4:7], v108 offset:4096
	ds_read_b128 v[8:11], v109 offset:4096
	s_waitcnt lgkmcnt(1)
	v_mfma_f32_32x32x16_bf16 v[48:63], v[4:7], v[84:87], v[48:63]
	s_waitcnt lgkmcnt(0)
	v_mfma_f32_32x32x16_bf16 v[48:63], v[8:11], v[80:83], v[48:63]
	ds_read_b128 v[4:7], v15 offset:8192
	ds_read_b128 v[8:11], v104 offset:8192
	s_waitcnt lgkmcnt(1)
	v_mfma_f32_32x32x16_bf16 v[32:47], v[4:7], v[0:3], 0
	s_waitcnt lgkmcnt(0)
	v_mfma_f32_32x32x16_bf16 v[32:47], v[8:11], v[88:91], v[32:47]
	ds_read_b128 v[4:7], v108 offset:8192
	ds_read_b128 v[8:11], v109 offset:8192
	s_waitcnt lgkmcnt(1)
	v_mfma_f32_32x32x16_bf16 v[32:47], v[4:7], v[84:87], v[32:47]
	s_waitcnt lgkmcnt(0)
	v_mfma_f32_32x32x16_bf16 v[32:47], v[8:11], v[80:83], v[32:47]
	ds_read_b128 v[4:7], v15 offset:12288
	ds_read_b128 v[8:11], v104 offset:12288
	s_waitcnt lgkmcnt(1)
	v_mfma_f32_32x32x16_bf16 v[16:31], v[4:7], v[0:3], 0
	s_waitcnt lgkmcnt(0)
	v_mfma_f32_32x32x16_bf16 v[16:31], v[8:11], v[88:91], v[16:31]
	ds_read_b128 v[4:7], v108 offset:12288
	ds_read_b128 v[8:11], v109 offset:12288
	s_waitcnt lgkmcnt(1)
	v_mfma_f32_32x32x16_bf16 v[16:31], v[4:7], v[84:87], v[16:31]
	s_waitcnt lgkmcnt(0)
	v_mfma_f32_32x32x16_bf16 v[16:31], v[8:11], v[80:83], v[16:31]
	ds_read_b128 v[4:7], v15 offset:16384
	ds_read_b128 v[104:107], v104 offset:16384
	s_waitcnt lgkmcnt(1)
	v_mfma_f32_32x32x16_bf16 v[0:15], v[4:7], v[0:3], 0
	s_waitcnt lgkmcnt(0)
	v_mfma_f32_32x32x16_bf16 v[0:15], v[104:107], v[88:91], v[0:15]
	ds_read_b128 v[88:91], v108 offset:16384
	ds_read_b128 v[104:107], v109 offset:16384
	s_waitcnt lgkmcnt(1)
	v_mfma_f32_32x32x16_bf16 v[0:15], v[88:91], v[84:87], v[0:15]
	s_waitcnt lgkmcnt(0)
	v_mfma_f32_32x32x16_bf16 v[0:15], v[104:107], v[80:83], v[0:15]
	v_lshlrev_b32_e32 v80, 2, v102
	v_add3_u32 v88, s46, v80, v92
	ds_read_b128 v[80:83], v88
	ds_read_b128 v[84:87], v88 offset:32
	s_waitcnt vmcnt(0)
	v_cvt_f32_i32_e32 v89, v103
	v_lshlrev_b32_e32 v90, 2, v101
	v_mul_f32_e32 v91, 0xbfb8aa3b, v110
	v_mul_f32_e32 v64, s76, v64
	s_waitcnt lgkmcnt(1)
	v_sub_f32_e32 v80, v89, v80
	v_fma_f32 v64, |v80|, v91, v64
	v_sub_f32_e32 v81, v89, v81
	v_mul_f32_e32 v65, s76, v65
	v_add_f32_e32 v80, v134, v64
	v_fma_f32 v65, |v81|, v91, v65
	v_mul_f32_e32 v66, s76, v66
	v_add_f32_e32 v81, v135, v65
	v_sub_f32_e32 v65, v89, v82
	v_fma_f32 v65, |v65|, v91, v66
	v_mul_f32_e32 v66, s76, v67
	v_add_f32_e32 v82, v136, v65
	v_sub_f32_e32 v65, v89, v83
	v_fma_f32 v65, |v65|, v91, v66
	v_mul_f32_e32 v66, s76, v68
	v_add_f32_e32 v83, v137, v65
	s_waitcnt lgkmcnt(0)
	v_sub_f32_e32 v65, v89, v84
	v_fma_f32 v65, |v65|, v91, v66
	v_mul_f32_e32 v66, s76, v69
	v_add_f32_e32 v84, v138, v65
	v_sub_f32_e32 v65, v89, v85
	v_max3_f32 v64, v80, s45, v81
	v_fma_f32 v65, |v65|, v91, v66
	v_max3_f32 v64, v64, v82, v83
	v_add_f32_e32 v85, v139, v65
	v_max3_f32 v68, v64, v84, v85
	v_sub_f32_e32 v64, v89, v86
	v_mul_f32_e32 v65, s76, v70
	v_fma_f32 v64, |v64|, v91, v65
	v_mul_f32_e32 v65, s76, v71
	v_add_f32_e32 v86, v140, v64
	v_sub_f32_e32 v64, v89, v87
	v_fma_f32 v69, |v64|, v91, v65
	ds_read_b128 v[64:67], v88 offset:64
	v_mul_f32_e32 v72, s76, v72
	v_add_f32_e32 v87, v141, v69
	v_max3_f32 v107, v68, v86, v87
	ds_read_b128 v[68:71], v88 offset:96
	s_waitcnt lgkmcnt(1)
	v_sub_f32_e32 v64, v89, v64
	v_fma_f32 v64, |v64|, v91, v72
	v_add_f32_e32 v72, v142, v64
	v_sub_f32_e32 v64, v89, v65
	v_mul_f32_e32 v65, s76, v73
	v_fma_f32 v64, |v64|, v91, v65
	v_sub_f32_e32 v65, v89, v66
	v_mul_f32_e32 v66, s76, v74
	v_add_f32_e32 v73, v143, v64
	v_max3_f32 v64, v107, v72, v73
	v_fma_f32 v65, |v65|, v91, v66
	v_mul_f32_e32 v66, s76, v75
	v_add_f32_e32 v74, v144, v65
	v_sub_f32_e32 v65, v89, v67
	v_fma_f32 v65, |v65|, v91, v66
	v_mul_f32_e32 v66, s76, v76
	v_add_f32_e32 v75, v145, v65
	s_waitcnt lgkmcnt(0)
	v_sub_f32_e32 v65, v89, v68
	v_fma_f32 v65, |v65|, v91, v66
	v_mul_f32_e32 v66, s76, v77
	v_add_f32_e32 v76, v148, v65
	v_sub_f32_e32 v65, v89, v69
	v_fma_f32 v65, |v65|, v91, v66
	v_mul_f32_e32 v66, s76, v78
	v_add_f32_e32 v77, v149, v65
	v_sub_f32_e32 v65, v89, v70
	v_fma_f32 v65, |v65|, v91, v66
	v_mul_f32_e32 v66, s76, v79
	v_max3_f32 v64, v64, v74, v75
	v_add_f32_e32 v78, v150, v65
	v_sub_f32_e32 v65, v89, v71
	v_fma_f32 v65, |v65|, v91, v66
	v_max3_f32 v64, v64, v76, v77
	s_nop 0
	v_add_f32_e32 v79, v152, v65
	v_max3_f32 v115, v64, v78, v79
	ds_read_b128 v[64:67], v88 offset:128
	ds_read_b128 v[68:71], v88 offset:160
	v_mul_f32_e32 v49, s76, v49
	v_mul_f32_e32 v50, s76, v50
	v_mul_f32_e32 v48, s76, v48
	s_waitcnt lgkmcnt(1)
; DI void unit(const bf16* __restrict__ QKV, const int* __restrict__ pos, bf16* __restrict__ OA, float* __restrict__ LSE,
;              int b, int h, int d, int r, int qb, float slope, char* lds) {
;     ...
;   for (int ta = 0; ta < 5; ++ta) {
; #pragma unroll
;     for (int g = 0; g < 4; ++g) { const f32x4 pk4 = *(const f32x4*)(pbase + ta * 32 + 8 * g);
; #pragma unroll
;       for (int j = 0; j < 4; ++j) { const int rr = 4 * g + j, kr = j + 8 * g + 4 * hi;
;         float sc = fmaf(__builtin_fabsf(pqf - pk4[j]), -sl2, p[ta][rr] * C);
;         if (ta == 0) sc = (kr >= r32) ? sc : -1e30f;
;         if (ta == 4) sc = (kr <= r32) ? sc : -1e30f;
;         p[ta][rr] = sc; mx = fmaxf(mx, sc); } }
	v_sub_f32_e32 v65, v89, v65
	v_fma_f32 v65, |v65|, v91, v49
	v_sub_f32_e32 v49, v89, v66
	v_sub_f32_e32 v64, v89, v64
	v_fma_f32 v66, |v49|, v91, v50
	v_sub_f32_e32 v49, v89, v67
	v_mul_f32_e32 v50, s76, v51
	v_fma_f32 v64, |v64|, v91, v48
	v_fma_f32 v67, |v49|, v91, v50
	s_waitcnt lgkmcnt(0)
	v_sub_f32_e32 v49, v89, v68
	v_mul_f32_e32 v50, s76, v52
	v_max3_f32 v48, v115, v64, v65
	v_fma_f32 v68, |v49|, v91, v50
	v_sub_f32_e32 v49, v89, v69
	v_mul_f32_e32 v50, s76, v53
	v_max3_f32 v48, v48, v66, v67
	v_fma_f32 v69, |v49|, v91, v50
	v_max3_f32 v52, v48, v68, v69
	v_sub_f32_e32 v48, v89, v70
	v_mul_f32_e32 v49, s76, v54
	v_fma_f32 v70, |v48|, v91, v49
	ds_read_b128 v[48:51], v88 offset:192
	v_sub_f32_e32 v53, v89, v71
	v_mul_f32_e32 v54, s76, v55
	v_fma_f32 v71, |v53|, v91, v54
	v_max3_f32 v115, v52, v70, v71
	ds_read_b128 v[52:55], v88 offset:224
	s_waitcnt lgkmcnt(1)
	v_sub_f32_e32 v48, v89, v48
	v_mul_f32_e32 v56, s76, v56
	v_fma_f32 v56, |v48|, v91, v56
	v_sub_f32_e32 v48, v89, v49
	v_mul_f32_e32 v49, s76, v57
	v_fma_f32 v57, |v48|, v91, v49
	v_sub_f32_e32 v49, v89, v50
	v_mul_f32_e32 v50, s76, v58
	v_fma_f32 v58, |v49|, v91, v50
	v_sub_f32_e32 v49, v89, v51
	v_mul_f32_e32 v50, s76, v59
	v_fma_f32 v59, |v49|, v91, v50
	s_waitcnt lgkmcnt(0)
	v_sub_f32_e32 v49, v89, v52
	v_mul_f32_e32 v50, s76, v60
	v_fma_f32 v60, |v49|, v91, v50
	v_sub_f32_e32 v49, v89, v53
	v_mul_f32_e32 v50, s76, v61
	v_max3_f32 v48, v115, v56, v57
	v_fma_f32 v61, |v49|, v91, v50
	v_sub_f32_e32 v49, v89, v54
	v_mul_f32_e32 v50, s76, v62
	v_max3_f32 v48, v48, v58, v59
	v_fma_f32 v62, |v49|, v91, v50
	v_sub_f32_e32 v49, v89, v55
	v_mul_f32_e32 v50, s76, v63
	v_max3_f32 v48, v48, v60, v61
	v_fma_f32 v63, |v49|, v91, v50
	v_max3_f32 v115, v48, v62, v63
	ds_read_b128 v[48:51], v88 offset:256
	ds_read_b128 v[52:55], v88 offset:288
	v_mul_f32_e32 v33, s76, v33
	v_mul_f32_e32 v34, s76, v34
	v_mul_f32_e32 v32, s76, v32
	s_waitcnt lgkmcnt(1)
	v_sub_f32_e32 v49, v89, v49
	v_fma_f32 v49, |v49|, v91, v33
	v_sub_f32_e32 v33, v89, v50
	v_sub_f32_e32 v48, v89, v48
	v_fma_f32 v50, |v33|, v91, v34
	v_sub_f32_e32 v33, v89, v51
	v_mul_f32_e32 v34, s76, v35
	v_fma_f32 v48, |v48|, v91, v32
	v_fma_f32 v51, |v33|, v91, v34
	s_waitcnt lgkmcnt(0)
	v_sub_f32_e32 v33, v89, v52
	v_mul_f32_e32 v34, s76, v36
	v_max3_f32 v32, v115, v48, v49
	v_fma_f32 v52, |v33|, v91, v34
	v_sub_f32_e32 v33, v89, v53
	v_mul_f32_e32 v34, s76, v37
	v_max3_f32 v32, v32, v50, v51
	v_fma_f32 v53, |v33|, v91, v34
	v_max3_f32 v36, v32, v52, v53
	v_sub_f32_e32 v32, v89, v54
	v_mul_f32_e32 v33, s76, v38
	v_fma_f32 v54, |v32|, v91, v33
	ds_read_b128 v[32:35], v88 offset:320
	v_sub_f32_e32 v37, v89, v55
	v_mul_f32_e32 v38, s76, v39
	v_fma_f32 v55, |v37|, v91, v38
	v_max3_f32 v115, v36, v54, v55
	ds_read_b128 v[36:39], v88 offset:352
	s_waitcnt lgkmcnt(1)
	v_sub_f32_e32 v32, v89, v32
	v_mul_f32_e32 v40, s76, v40
	v_fma_f32 v40, |v32|, v91, v40
	v_sub_f32_e32 v32, v89, v33
	v_mul_f32_e32 v33, s76, v41
	v_fma_f32 v41, |v32|, v91, v33
	v_sub_f32_e32 v33, v89, v34
	v_mul_f32_e32 v34, s76, v42
	v_fma_f32 v42, |v33|, v91, v34
	v_sub_f32_e32 v33, v89, v35
	v_mul_f32_e32 v34, s76, v43
	v_fma_f32 v43, |v33|, v91, v34
	s_waitcnt lgkmcnt(0)
	v_sub_f32_e32 v33, v89, v36
	v_mul_f32_e32 v34, s76, v44
	v_fma_f32 v44, |v33|, v91, v34
	v_sub_f32_e32 v33, v89, v37
	v_mul_f32_e32 v34, s76, v45
	v_max3_f32 v32, v115, v40, v41
	v_fma_f32 v45, |v33|, v91, v34
	v_sub_f32_e32 v33, v89, v38
	v_mul_f32_e32 v34, s76, v46
	v_max3_f32 v32, v32, v42, v43
	v_fma_f32 v46, |v33|, v91, v34
	v_sub_f32_e32 v33, v89, v39
	v_mul_f32_e32 v34, s76, v47
	v_max3_f32 v32, v32, v44, v45
	v_fma_f32 v47, |v33|, v91, v34
	v_max3_f32 v115, v32, v46, v47
	ds_read_b128 v[32:35], v88 offset:384
	ds_read_b128 v[36:39], v88 offset:416
	v_mul_f32_e32 v17, s76, v17
	v_mul_f32_e32 v18, s76, v18
	v_mul_f32_e32 v16, s76, v16
	s_waitcnt lgkmcnt(1)
	v_sub_f32_e32 v33, v89, v33
	v_fma_f32 v33, |v33|, v91, v17
	v_sub_f32_e32 v17, v89, v34
	v_sub_f32_e32 v32, v89, v32
	v_fma_f32 v34, |v17|, v91, v18
	v_sub_f32_e32 v17, v89, v35
	v_mul_f32_e32 v18, s76, v19
	v_fma_f32 v116, |v32|, v91, v16
	v_fma_f32 v35, |v17|, v91, v18
	s_waitcnt lgkmcnt(0)
	v_sub_f32_e32 v17, v89, v36
	v_mul_f32_e32 v18, s76, v20
	v_max3_f32 v16, v115, v116, v33
	v_fma_f32 v36, |v17|, v91, v18
	v_sub_f32_e32 v17, v89, v37
	v_mul_f32_e32 v18, s76, v21
	v_max3_f32 v16, v16, v34, v35
	v_fma_f32 v37, |v17|, v91, v18
	v_max3_f32 v20, v16, v36, v37
	v_sub_f32_e32 v16, v89, v38
	v_mul_f32_e32 v17, s76, v22
	v_fma_f32 v38, |v16|, v91, v17
	ds_read_b128 v[16:19], v88 offset:448
	v_sub_f32_e32 v21, v89, v39
	v_mul_f32_e32 v22, s76, v23
	v_fma_f32 v39, |v21|, v91, v22
	v_max3_f32 v32, v20, v38, v39
	ds_read_b128 v[20:23], v88 offset:480
	s_waitcnt lgkmcnt(1)
	v_sub_f32_e32 v16, v89, v16
	v_mul_f32_e32 v24, s76, v24
	v_fma_f32 v24, |v16|, v91, v24
	v_sub_f32_e32 v16, v89, v17
	v_mul_f32_e32 v17, s76, v25
	v_fma_f32 v25, |v16|, v91, v17
	v_sub_f32_e32 v17, v89, v18
	v_mul_f32_e32 v18, s76, v26
	v_fma_f32 v26, |v17|, v91, v18
	v_sub_f32_e32 v17, v89, v19
	v_mul_f32_e32 v18, s76, v27
	v_fma_f32 v27, |v17|, v91, v18
	s_waitcnt lgkmcnt(0)
	v_sub_f32_e32 v17, v89, v20
	v_mul_f32_e32 v18, s76, v28
	v_fma_f32 v28, |v17|, v91, v18
	v_sub_f32_e32 v17, v89, v21
	v_mul_f32_e32 v18, s76, v29
	v_max3_f32 v16, v32, v24, v25
	v_fma_f32 v29, |v17|, v91, v18
	v_sub_f32_e32 v17, v89, v22
	v_mul_f32_e32 v18, s76, v30
	v_max3_f32 v16, v16, v26, v27
	v_fma_f32 v30, |v17|, v91, v18
	v_sub_f32_e32 v17, v89, v23
	v_mul_f32_e32 v18, s76, v31
	v_max3_f32 v16, v16, v28, v29
	v_fma_f32 v31, |v17|, v91, v18
	v_max3_f32 v32, v16, v30, v31
	ds_read_b128 v[16:19], v88 offset:512
	ds_read_b128 v[20:23], v88 offset:544
	v_mul_f32_e32 v0, s76, v0
	v_mul_f32_e32 v2, s76, v2
	s_waitcnt lgkmcnt(1)
; #define SBAR() __builtin_amdgcn_sched_barrier(0)
; DI void unit(const bf16* __restrict__ QKV, const int* __restrict__ pos, bf16* __restrict__ OA, float* __restrict__ LSE,
;              int b, int h, int d, int r, int qb, float slope, char* lds) {
;     ...
;   for (int ta = 0; ta < 5; ++ta) {
; #pragma unroll
;     for (int g = 0; g < 4; ++g) { const f32x4 pk4 = *(const f32x4*)(pbase + ta * 32 + 8 * g);
; #pragma unroll
;       for (int j = 0; j < 4; ++j) { const int rr = 4 * g + j, kr = j + 8 * g + 4 * hi;
;         float sc = fmaf(__builtin_fabsf(pqf - pk4[j]), -sl2, p[ta][rr] * C);
;         if (ta == 0) sc = (kr >= r32) ? sc : -1e30f;
;         if (ta == 4) sc = (kr <= r32) ? sc : -1e30f;
;         p[ta][rr] = sc; mx = fmaxf(mx, sc); } }
;     SBAR(); }
;   { auto x = __builtin_amdgcn_permlane32_swap(__float_as_uint(mx), __float_as_uint(mx), false, false); mx = fmaxf(__uint_as_float(x[0]), __uint_as_float(x[1])); }
;   float ls = 0.f;
; #pragma unroll
;   for (int ta = 0; ta < 5; ++ta)
; #pragma unroll
;     for (int rr = 0; rr < 16; ++rr) { p[ta][rr] = __builtin_amdgcn_exp2f(p[ta][rr] - mx); ls += p[ta][rr]; if (rr == 15) SBAR(); }
;   { auto x = __builtin_amdgcn_permlane32_swap(__float_as_uint(ls), __float_as_uint(ls), false, false); ls = __uint_as_float(x[0]) + __uint_as_float(x[1]); }
	v_sub_f32_e32 v16, v89, v16
	v_fma_f32 v0, |v16|, v91, v0
	v_sub_f32_e32 v17, v89, v17
	v_add_f32_e32 v16, v153, v0
	v_mul_f32_e32 v0, s76, v1
	v_fma_f32 v0, |v17|, v91, v0
	v_sub_f32_e32 v1, v89, v18
	v_add_f32_e32 v17, v154, v0
	v_fma_f32 v1, |v1|, v91, v2
	v_mul_f32_e32 v2, s76, v3
	v_max3_f32 v0, v32, v16, v17
	v_add_f32_e32 v18, v155, v1
	v_sub_f32_e32 v1, v89, v19
	v_fma_f32 v1, |v1|, v91, v2
	v_mul_f32_e32 v2, s76, v4
	v_mul_f32_e32 v8, s76, v8
	v_add_f32_e32 v19, v156, v1
	s_waitcnt lgkmcnt(0)
	v_sub_f32_e32 v1, v89, v20
	v_fma_f32 v1, |v1|, v91, v2
	v_mul_f32_e32 v2, s76, v5
	v_max3_f32 v0, v0, v18, v19
	v_add_f32_e32 v20, v157, v1
	v_sub_f32_e32 v1, v89, v21
	v_fma_f32 v1, |v1|, v91, v2
	s_nop 1
	v_add_f32_e32 v21, v158, v1
	v_max3_f32 v4, v0, v20, v21
	v_sub_f32_e32 v0, v89, v22
	v_mul_f32_e32 v1, s76, v6
	v_fma_f32 v0, |v0|, v91, v1
	v_mul_f32_e32 v1, s76, v7
	s_nop 0
	v_add_f32_e32 v22, v159, v0
	v_sub_f32_e32 v0, v89, v23
	v_fma_f32 v5, |v0|, v91, v1
	ds_read_b128 v[0:3], v88 offset:576
	s_nop 1
	v_add_f32_e32 v23, v162, v5
	v_max3_f32 v32, v4, v22, v23
	ds_read_b128 v[4:7], v88 offset:608
	s_waitcnt lgkmcnt(1)
	v_sub_f32_e32 v0, v89, v0
	v_fma_f32 v0, |v0|, v91, v8
	v_sub_f32_e32 v1, v89, v1
	v_mul_f32_e32 v8, s76, v9
	v_add_f32_e32 v0, v163, v0
	v_fma_f32 v1, |v1|, v91, v8
	v_sub_f32_e32 v2, v89, v2
	v_mul_f32_e32 v9, s76, v10
	v_add_f32_e32 v1, v227, v1
	v_fma_f32 v2, |v2|, v91, v9
	v_sub_f32_e32 v3, v89, v3
	v_mul_f32_e32 v9, s76, v11
	v_add_f32_e32 v2, v228, v2
	v_fma_f32 v3, |v3|, v91, v9
	s_waitcnt lgkmcnt(0)
	v_sub_f32_e32 v4, v89, v4
	v_mul_f32_e32 v9, s76, v12
	v_add_f32_e32 v3, v229, v3
	v_fma_f32 v4, |v4|, v91, v9
	v_sub_f32_e32 v5, v89, v5
	v_mul_f32_e32 v9, s76, v13
	v_add_f32_e32 v4, v230, v4
	v_fma_f32 v5, |v5|, v91, v9
	v_sub_f32_e32 v6, v89, v6
	v_mul_f32_e32 v9, s76, v14
	v_max3_f32 v8, v32, v0, v1
	v_add_f32_e32 v5, v231, v5
	v_fma_f32 v6, |v6|, v91, v9
	v_sub_f32_e32 v7, v89, v7
	v_mul_f32_e32 v9, s76, v15
	v_max3_f32 v8, v8, v2, v3
	v_add_f32_e32 v6, v232, v6
	v_fma_f32 v7, |v7|, v91, v9
	v_max3_f32 v8, v8, v4, v5
	s_nop 0
	v_add_f32_e32 v7, v233, v7
	v_max3_f32 v8, v8, v6, v7
	v_mov_b32_e32 v9, v8
	s_nop 1
	v_permlane32_swap_b32_e32 v8, v9
	v_max_f32_e32 v9, v9, v9
	v_max_f32_e32 v8, v8, v8
	v_max_f32_e32 v32, v8, v9
	v_sub_f32_e32 v8, v80, v32
	v_exp_f32_e32 v8, v8
	v_sub_f32_e32 v9, v81, v32
	v_exp_f32_e32 v9, v9
	v_sub_f32_e32 v10, v82, v32
	v_exp_f32_e32 v10, v10
	v_sub_f32_e32 v11, v83, v32
	v_exp_f32_e32 v11, v11
	v_sub_f32_e32 v12, v84, v32
	v_exp_f32_e32 v12, v12
	v_sub_f32_e32 v13, v85, v32
	v_add_f32_e32 v80, 0, v8
	v_exp_f32_e32 v13, v13
	v_sub_f32_e32 v14, v86, v32
	v_add_f32_e32 v80, v9, v80
	v_exp_f32_e32 v14, v14
	v_sub_f32_e32 v15, v87, v32
	v_add_f32_e32 v80, v10, v80
	v_exp_f32_e32 v15, v15
	v_sub_f32_e32 v72, v72, v32
	v_add_f32_e32 v80, v11, v80
	v_exp_f32_e32 v72, v72
	v_sub_f32_e32 v73, v73, v32
	v_add_f32_e32 v80, v12, v80
	v_exp_f32_e32 v73, v73
	v_sub_f32_e32 v74, v74, v32
	v_add_f32_e32 v80, v13, v80
	v_exp_f32_e32 v74, v74
	v_sub_f32_e32 v75, v75, v32
	v_add_f32_e32 v80, v14, v80
	v_exp_f32_e32 v75, v75
	v_sub_f32_e32 v76, v76, v32
	v_add_f32_e32 v80, v15, v80
	v_exp_f32_e32 v76, v76
	v_sub_f32_e32 v77, v77, v32
	v_add_f32_e32 v80, v72, v80
	v_exp_f32_e32 v77, v77
	v_sub_f32_e32 v78, v78, v32
	v_add_f32_e32 v80, v73, v80
	v_exp_f32_e32 v78, v78
	v_add_f32_e32 v80, v74, v80
	v_sub_f32_e32 v79, v79, v32
	v_add_f32_e32 v80, v75, v80
	v_exp_f32_e32 v79, v79
	v_add_f32_e32 v80, v76, v80
	v_add_f32_e32 v80, v77, v80
	v_add_f32_e32 v80, v78, v80
	v_add_f32_e32 v80, v79, v80
	v_sub_f32_e32 v64, v64, v32
	v_exp_f32_e32 v64, v64
	v_sub_f32_e32 v65, v65, v32
	v_exp_f32_e32 v65, v65
	v_sub_f32_e32 v66, v66, v32
	v_exp_f32_e32 v66, v66
	v_sub_f32_e32 v67, v67, v32
	v_exp_f32_e32 v67, v67
	v_sub_f32_e32 v68, v68, v32
	v_exp_f32_e32 v68, v68
	v_sub_f32_e32 v69, v69, v32
	v_add_f32_e32 v80, v64, v80
	v_exp_f32_e32 v69, v69
	v_sub_f32_e32 v70, v70, v32
	v_add_f32_e32 v80, v65, v80
	v_exp_f32_e32 v70, v70
	v_sub_f32_e32 v71, v71, v32
	v_add_f32_e32 v80, v66, v80
	v_exp_f32_e32 v71, v71
	v_sub_f32_e32 v56, v56, v32
	v_add_f32_e32 v80, v67, v80
	v_exp_f32_e32 v56, v56
	v_sub_f32_e32 v57, v57, v32
	v_add_f32_e32 v80, v68, v80
	v_exp_f32_e32 v57, v57
	v_sub_f32_e32 v58, v58, v32
	v_add_f32_e32 v80, v69, v80
	v_exp_f32_e32 v58, v58
	v_sub_f32_e32 v59, v59, v32
	v_add_f32_e32 v80, v70, v80
	v_exp_f32_e32 v59, v59
	v_sub_f32_e32 v60, v60, v32
	v_add_f32_e32 v80, v71, v80
	v_exp_f32_e32 v60, v60
	v_sub_f32_e32 v61, v61, v32
	v_add_f32_e32 v80, v56, v80
	v_exp_f32_e32 v61, v61
	v_sub_f32_e32 v62, v62, v32
	v_add_f32_e32 v80, v57, v80
	v_exp_f32_e32 v62, v62
	v_add_f32_e32 v80, v58, v80
	v_sub_f32_e32 v63, v63, v32
	v_add_f32_e32 v80, v59, v80
	v_exp_f32_e32 v63, v63
	v_add_f32_e32 v80, v60, v80
	v_add_f32_e32 v80, v61, v80
	v_add_f32_e32 v80, v62, v80
	v_add_f32_e32 v80, v63, v80
	v_sub_f32_e32 v40, v40, v32
	v_exp_f32_e32 v87, v40
	v_sub_f32_e32 v40, v41, v32
	v_sub_f32_e32 v48, v48, v32
	v_exp_f32_e32 v88, v40
	v_sub_f32_e32 v40, v42, v32
	v_exp_f32_e32 v81, v48
	v_sub_f32_e32 v48, v49, v32
	v_exp_f32_e32 v89, v40
	v_sub_f32_e32 v40, v43, v32
	v_exp_f32_e32 v82, v48
	v_sub_f32_e32 v48, v50, v32
	v_exp_f32_e32 v90, v40
	v_sub_f32_e32 v40, v44, v32
	v_exp_f32_e32 v83, v48
	v_sub_f32_e32 v48, v51, v32
	v_exp_f32_e32 v91, v40
	v_sub_f32_e32 v40, v45, v32
	v_exp_f32_e32 v84, v48
	v_sub_f32_e32 v48, v52, v32
	v_exp_f32_e32 v100, v40
	v_sub_f32_e32 v40, v46, v32
	v_exp_f32_e32 v85, v48
	v_sub_f32_e32 v48, v53, v32
	v_exp_f32_e32 v101, v40
	v_add_f32_e32 v40, v81, v80
	v_exp_f32_e32 v86, v48
; #define SBAR() __builtin_amdgcn_sched_barrier(0)
; DI int v_rd_base(int lane) { return ((lane & 3) << 3) | (((lane >> 2) & 3) << 6) | (((lane >> 4) & 1) << 5) | (((lane >> 5) & 1) << 8); }
; DI s16x4 vtr(const char* p) { return __builtin_bit_cast(s16x4, __builtin_amdgcn_ds_read_tr16_b64_v4i16((LAS v4i16_t*)(uintptr_t)p)); }
; DI void unit(const bf16* __restrict__ QKV, const int* __restrict__ pos, bf16* __restrict__ OA, float* __restrict__ LSE,
;              int b, int h, int d, int r, int qb, float slope, char* lds) {
;     ...
;   float ls = 0.f;
; #pragma unroll
;   for (int ta = 0; ta < 5; ++ta)
; #pragma unroll
;     for (int rr = 0; rr < 16; ++rr) { p[ta][rr] = __builtin_amdgcn_exp2f(p[ta][rr] - mx); ls += p[ta][rr]; if (rr == 15) SBAR(); }
;   { auto x = __builtin_amdgcn_permlane32_swap(__float_as_uint(ls), __float_as_uint(ls), false, false); ls = __uint_as_float(x[0]) + __uint_as_float(x[1]); }
;   f32x16 o[2] = {};
;   const char* vb = V_lds + att::v_rd_base(lane) + wid * 2 * 2048;
; #pragma unroll
;   for (int ta = 0; ta < 5; ++ta) {
;     bf16x8 pa0, pa1; PK4(p[ta], 0, pa0); PK4(p[ta], 8, pa1);
; #pragma unroll
;     for (int d0 = 0; d0 < 2; ++d0) {
;       const s16x4 l0 = vtr(vb + (2 * ta) * 2048 + d0 * 512), h0 = vtr(vb + (2 * ta) * 2048 + 1024 + d0 * 512);
;       const s16x4 l1 = vtr(vb + (2 * ta + 1) * 2048 + d0 * 512), h1 = vtr(vb + (2 * ta + 1) * 2048 + 1024 + d0 * 512);
;       o[d0] = __builtin_amdgcn_mfma_f32_32x32x16_bf16((bf16x8){l0[0], l0[1], l0[2], l0[3], h0[0], h0[1], h0[2], h0[3]}, pa0, o[d0], 0, 0, 0);
;       o[d0] = __builtin_amdgcn_mfma_f32_32x32x16_bf16((bf16x8){l1[0], l1[1], l1[2], l1[3], h1[0], h1[1], h1[2], h1[3]}, pa1, o[d0], 0, 0, 0);
	v_sub_f32_e32 v48, v54, v32
	v_add_f32_e32 v40, v82, v40
	v_exp_f32_e32 v54, v48
	v_sub_f32_e32 v48, v55, v32
	v_add_f32_e32 v40, v83, v40
	v_exp_f32_e32 v55, v48
	v_add_f32_e32 v40, v84, v40
	v_add_f32_e32 v40, v85, v40
	v_add_f32_e32 v40, v86, v40
	v_add_f32_e32 v40, v54, v40
	v_add_f32_e32 v40, v55, v40
	v_add_f32_e32 v40, v87, v40
	v_add_f32_e32 v40, v88, v40
	v_add_f32_e32 v40, v89, v40
	v_sub_f32_e32 v41, v47, v32
	v_add_f32_e32 v40, v90, v40
	v_exp_f32_e32 v80, v41
	v_add_f32_e32 v40, v91, v40
	v_add_f32_e32 v40, v100, v40
	v_add_f32_e32 v40, v101, v40
	v_add_f32_e32 v40, v80, v40
	v_sub_f32_e32 v24, v24, v32
	v_exp_f32_e32 v109, v24
	v_sub_f32_e32 v24, v25, v32
	v_sub_f32_e32 v41, v116, v32
	v_exp_f32_e32 v110, v24
	v_sub_f32_e32 v24, v26, v32
	v_exp_f32_e32 v102, v41
	v_sub_f32_e32 v33, v33, v32
	v_exp_f32_e32 v111, v24
	v_sub_f32_e32 v24, v27, v32
	v_exp_f32_e32 v33, v33
	v_sub_f32_e32 v34, v34, v32
	v_exp_f32_e32 v112, v24
	v_sub_f32_e32 v24, v28, v32
	v_exp_f32_e32 v103, v34
	v_sub_f32_e32 v34, v35, v32
	v_exp_f32_e32 v113, v24
	v_sub_f32_e32 v24, v29, v32
	v_exp_f32_e32 v104, v34
	v_sub_f32_e32 v34, v36, v32
	v_exp_f32_e32 v114, v24
	v_sub_f32_e32 v24, v30, v32
	v_exp_f32_e32 v105, v34
	v_sub_f32_e32 v34, v37, v32
	v_exp_f32_e32 v115, v24
	v_add_f32_e32 v24, v102, v40
	v_exp_f32_e32 v106, v34
	v_sub_f32_e32 v34, v38, v32
	v_add_f32_e32 v24, v33, v24
	v_exp_f32_e32 v107, v34
	v_sub_f32_e32 v34, v39, v32
	v_add_f32_e32 v24, v103, v24
	v_exp_f32_e32 v108, v34
	v_add_f32_e32 v24, v104, v24
	v_add_f32_e32 v24, v105, v24
	v_add_f32_e32 v24, v106, v24
	v_add_f32_e32 v24, v107, v24
	v_add_f32_e32 v24, v108, v24
	v_add_f32_e32 v24, v109, v24
	v_add_f32_e32 v24, v110, v24
	v_add_f32_e32 v24, v111, v24
	v_sub_f32_e32 v25, v31, v32
	v_add_f32_e32 v24, v112, v24
	v_exp_f32_e32 v116, v25
	v_add_f32_e32 v24, v113, v24
	v_add_f32_e32 v24, v114, v24
	v_add_f32_e32 v24, v115, v24
	v_add_f32_e32 v24, v116, v24
	v_sub_f32_e32 v0, v0, v32
	v_exp_f32_e32 v125, v0
	v_sub_f32_e32 v0, v1, v32
	v_sub_f32_e32 v16, v16, v32
	v_exp_f32_e32 v126, v0
	v_sub_f32_e32 v0, v2, v32
	v_exp_f32_e32 v117, v16
	v_sub_f32_e32 v16, v17, v32
	v_exp_f32_e32 v127, v0
	v_sub_f32_e32 v0, v3, v32
	v_exp_f32_e32 v118, v16
	v_sub_f32_e32 v16, v18, v32
	v_exp_f32_e32 v128, v0
	v_sub_f32_e32 v0, v4, v32
	v_exp_f32_e32 v119, v16
	v_sub_f32_e32 v16, v19, v32
	v_exp_f32_e32 v129, v0
	v_sub_f32_e32 v0, v5, v32
	v_exp_f32_e32 v120, v16
	v_sub_f32_e32 v16, v20, v32
	v_exp_f32_e32 v130, v0
	v_sub_f32_e32 v0, v6, v32
	v_exp_f32_e32 v121, v16
	v_sub_f32_e32 v16, v21, v32
	v_exp_f32_e32 v131, v0
	v_add_f32_e32 v0, v117, v24
	v_exp_f32_e32 v122, v16
	v_sub_f32_e32 v16, v22, v32
	v_add_f32_e32 v0, v118, v0
	v_exp_f32_e32 v123, v16
	v_sub_f32_e32 v16, v23, v32
	v_add_f32_e32 v0, v119, v0
	v_exp_f32_e32 v124, v16
	v_add_f32_e32 v0, v120, v0
	v_add_f32_e32 v0, v121, v0
	v_add_f32_e32 v0, v122, v0
	v_add_f32_e32 v0, v123, v0
	v_add_f32_e32 v0, v124, v0
	v_add_f32_e32 v0, v125, v0
	v_add_f32_e32 v0, v126, v0
	v_add_f32_e32 v0, v127, v0
	v_sub_f32_e32 v1, v7, v32
	v_add_f32_e32 v0, v128, v0
	v_exp_f32_e32 v132, v1
	v_add_f32_e32 v0, v129, v0
	v_add_f32_e32 v0, v130, v0
	v_add_f32_e32 v0, v131, v0
	v_add_f32_e32 v133, v132, v0
	v_lshlrev_b32_e32 v0, 3, v98
	v_and_b32_e32 v1, 24, v0
	v_lshlrev_b32_e32 v2, 4, v98
	v_lshlrev_b32_e32 v3, 1, v98
	v_and_b32_e32 v2, 0xc0, v2
	v_and_b32_e32 v3, 32, v3
	v_add_u32_e32 v1, 0, v1
	v_and_b32_e32 v0, 0x100, v0
	v_add3_u32 v1, v1, v2, v3
	v_add3_u32 v99, v1, v0, v99
	v_cvt_pk_bf16_f32 v0, v8, v9
	v_cvt_pk_bf16_f32 v1, v10, v11
	v_cvt_pk_bf16_f32 v2, v12, v13
	v_cvt_pk_bf16_f32 v3, v14, v15
	v_cvt_pk_bf16_f32 v34, v72, v73
	v_cvt_pk_bf16_f32 v35, v74, v75
	v_cvt_pk_bf16_f32 v36, v76, v77
	v_cvt_pk_bf16_f32 v37, v78, v79
	ds_read_b64_tr_b16 v[4:5], v99 offset:49152
	ds_read_b64_tr_b16 v[6:7], v99 offset:50176
	v_permlane32_swap_b32_e32 v0, v2
	v_permlane32_swap_b32_e32 v1, v3
	ds_read_b64_tr_b16 v[10:11], v99 offset:50688
	ds_read_b64_tr_b16 v[8:9], v99 offset:49664
	s_waitcnt lgkmcnt(2)
	v_mfma_f32_32x32x16_bf16 v[16:31], v[4:7], v[0:3], 0
	ds_read_b64_tr_b16 v[4:5], v99 offset:51200
	ds_read_b64_tr_b16 v[6:7], v99 offset:52224
	v_permlane32_swap_b32_e32 v34, v36
	v_permlane32_swap_b32_e32 v35, v37
	ds_read_b64_tr_b16 v[40:41], v99 offset:52736
	ds_read_b64_tr_b16 v[38:39], v99 offset:51712
	v_mov_b32_e32 v72, v133
	s_waitcnt lgkmcnt(2)
	v_mfma_f32_32x32x16_bf16 v[16:31], v[4:7], v[34:37], v[16:31]
	v_permlane32_swap_b32_e32 v133, v72
	v_add_u32_e32 v73, 0xc000, v99
	v_mfma_f32_32x32x16_bf16 v[0:15], v[8:11], v[0:3], 0
	s_waitcnt lgkmcnt(0)
; #define SBAR() __builtin_amdgcn_sched_barrier(0)
; DI int v_rd_base(int lane) { return ((lane & 3) << 3) | (((lane >> 2) & 3) << 6) | (((lane >> 4) & 1) << 5) | (((lane >> 5) & 1) << 8); }
; DI s16x4 vtr(const char* p) { return __builtin_bit_cast(s16x4, __builtin_amdgcn_ds_read_tr16_b64_v4i16((LAS v4i16_t*)(uintptr_t)p)); }
; DI void unit(const bf16* __restrict__ QKV, const int* __restrict__ pos, bf16* __restrict__ OA, float* __restrict__ LSE,
;              int b, int h, int d, int r, int qb, float slope, char* lds) {
;     ...
;   f32x16 o[2] = {};
;   const char* vb = V_lds + att::v_rd_base(lane) + wid * 2 * 2048;
; #pragma unroll
;   for (int ta = 0; ta < 5; ++ta) {
;     bf16x8 pa0, pa1; PK4(p[ta], 0, pa0); PK4(p[ta], 8, pa1);
; #pragma unroll
;     for (int d0 = 0; d0 < 2; ++d0) {
;       const s16x4 l0 = vtr(vb + (2 * ta) * 2048 + d0 * 512), h0 = vtr(vb + (2 * ta) * 2048 + 1024 + d0 * 512);
;       const s16x4 l1 = vtr(vb + (2 * ta + 1) * 2048 + d0 * 512), h1 = vtr(vb + (2 * ta + 1) * 2048 + 1024 + d0 * 512);
;       o[d0] = __builtin_amdgcn_mfma_f32_32x32x16_bf16((bf16x8){l0[0], l0[1], l0[2], l0[3], h0[0], h0[1], h0[2], h0[3]}, pa0, o[d0], 0, 0, 0);
;       o[d0] = __builtin_amdgcn_mfma_f32_32x32x16_bf16((bf16x8){l1[0], l1[1], l1[2], l1[3], h1[0], h1[1], h1[2], h1[3]}, pa1, o[d0], 0, 0, 0);
;     }
;     SBAR();
;   }
;   if (hi == 0) LSE[(size_t)(b * SEQ + tq) * 8 + h] = (mx + __builtin_amdgcn_logf(ls)) * 0.6931471805599453f;
	v_mfma_f32_32x32x16_bf16 v[0:15], v[38:41], v[34:37], v[0:15]
	v_cvt_pk_bf16_f32 v34, v64, v65
	v_cvt_pk_bf16_f32 v35, v66, v67
	v_cvt_pk_bf16_f32 v36, v68, v69
	v_cvt_pk_bf16_f32 v37, v70, v71
	v_cvt_pk_bf16_f32 v38, v56, v57
	v_cvt_pk_bf16_f32 v39, v58, v59
	v_cvt_pk_bf16_f32 v40, v60, v61
	v_cvt_pk_bf16_f32 v41, v62, v63
	ds_read_b64_tr_b16 v[42:43], v99 offset:53248
	ds_read_b64_tr_b16 v[44:45], v99 offset:54272
	ds_read_b64_tr_b16 v[48:49], v99 offset:54784
	ds_read_b64_tr_b16 v[46:47], v99 offset:53760
	v_permlane32_swap_b32_e32 v34, v36
	v_permlane32_swap_b32_e32 v35, v37
	v_permlane32_swap_b32_e32 v38, v40
	s_waitcnt lgkmcnt(2)
	v_mfma_f32_32x32x16_bf16 v[16:31], v[42:45], v[34:37], v[16:31]
	ds_read_b64_tr_b16 v[42:43], v99 offset:55296
	ds_read_b64_tr_b16 v[44:45], v99 offset:56320
	ds_read_b64_tr_b16 v[52:53], v99 offset:56832
	ds_read_b64_tr_b16 v[50:51], v99 offset:55808
	v_permlane32_swap_b32_e32 v39, v41
	s_waitcnt lgkmcnt(4)
	v_mfma_f32_32x32x16_bf16 v[0:15], v[46:49], v[34:37], v[0:15]
	s_waitcnt lgkmcnt(2)
	v_mfma_f32_32x32x16_bf16 v[16:31], v[42:45], v[38:41], v[16:31]
	s_waitcnt lgkmcnt(0)
	v_mfma_f32_32x32x16_bf16 v[0:15], v[50:53], v[38:41], v[0:15]
	v_cvt_pk_bf16_f32 v34, v81, v82
	v_cvt_pk_bf16_f32 v35, v83, v84
	v_cvt_pk_bf16_f32 v36, v85, v86
	v_cvt_pk_bf16_f32 v37, v54, v55
	v_cvt_pk_bf16_f32 v38, v87, v88
	v_cvt_pk_bf16_f32 v39, v89, v90
	v_cvt_pk_bf16_f32 v40, v91, v100
	v_cvt_pk_bf16_f32 v41, v101, v80
	ds_read_b64_tr_b16 v[42:43], v99 offset:57344
	ds_read_b64_tr_b16 v[44:45], v99 offset:58368
	ds_read_b64_tr_b16 v[48:49], v99 offset:58880
	ds_read_b64_tr_b16 v[46:47], v99 offset:57856
	v_permlane32_swap_b32_e32 v34, v36
	v_permlane32_swap_b32_e32 v35, v37
	v_permlane32_swap_b32_e32 v38, v40
	s_waitcnt lgkmcnt(2)
	v_mfma_f32_32x32x16_bf16 v[16:31], v[42:45], v[34:37], v[16:31]
	ds_read_b64_tr_b16 v[42:43], v99 offset:59392
	ds_read_b64_tr_b16 v[44:45], v99 offset:60416
	ds_read_b64_tr_b16 v[52:53], v99 offset:60928
	ds_read_b64_tr_b16 v[50:51], v99 offset:59904
	v_permlane32_swap_b32_e32 v39, v41
	s_waitcnt lgkmcnt(4)
	v_mfma_f32_32x32x16_bf16 v[0:15], v[46:49], v[34:37], v[0:15]
	s_waitcnt lgkmcnt(2)
	v_mfma_f32_32x32x16_bf16 v[16:31], v[42:45], v[38:41], v[16:31]
	s_waitcnt lgkmcnt(0)
	v_mfma_f32_32x32x16_bf16 v[0:15], v[50:53], v[38:41], v[0:15]
	v_cvt_pk_bf16_f32 v34, v102, v33
	v_cvt_pk_bf16_f32 v35, v103, v104
	v_cvt_pk_bf16_f32 v36, v105, v106
	v_cvt_pk_bf16_f32 v37, v107, v108
	v_cvt_pk_bf16_f32 v38, v109, v110
	v_cvt_pk_bf16_f32 v39, v111, v112
	v_cvt_pk_bf16_f32 v40, v113, v114
	v_cvt_pk_bf16_f32 v41, v115, v116
	ds_read_b64_tr_b16 v[42:43], v99 offset:61440
	ds_read_b64_tr_b16 v[44:45], v99 offset:62464
	ds_read_b64_tr_b16 v[48:49], v99 offset:62976
	ds_read_b64_tr_b16 v[46:47], v99 offset:61952
	v_permlane32_swap_b32_e32 v34, v36
	v_permlane32_swap_b32_e32 v35, v37
	v_permlane32_swap_b32_e32 v38, v40
	s_waitcnt lgkmcnt(2)
	v_mfma_f32_32x32x16_bf16 v[16:31], v[42:45], v[34:37], v[16:31]
	ds_read_b64_tr_b16 v[42:43], v99 offset:63488
	ds_read_b64_tr_b16 v[44:45], v99 offset:64512
	ds_read_b64_tr_b16 v[52:53], v99 offset:65024
	ds_read_b64_tr_b16 v[50:51], v99 offset:64000
	v_permlane32_swap_b32_e32 v39, v41
	s_waitcnt lgkmcnt(4)
	v_mfma_f32_32x32x16_bf16 v[0:15], v[46:49], v[34:37], v[0:15]
	s_waitcnt lgkmcnt(2)
	v_mfma_f32_32x32x16_bf16 v[16:31], v[42:45], v[38:41], v[16:31]
	s_waitcnt lgkmcnt(0)
	v_mfma_f32_32x32x16_bf16 v[0:15], v[50:53], v[38:41], v[0:15]
	v_cvt_pk_bf16_f32 v34, v117, v118
	v_cvt_pk_bf16_f32 v35, v119, v120
	v_cvt_pk_bf16_f32 v36, v121, v122
	v_cvt_pk_bf16_f32 v37, v123, v124
	v_cvt_pk_bf16_f32 v38, v125, v126
	v_cvt_pk_bf16_f32 v39, v127, v128
	v_cvt_pk_bf16_f32 v40, v129, v130
	v_cvt_pk_bf16_f32 v41, v131, v132
	ds_read_b64_tr_b16 v[42:43], v73 offset:16384
	ds_read_b64_tr_b16 v[44:45], v73 offset:17408
	ds_read_b64_tr_b16 v[48:49], v73 offset:17920
	ds_read_b64_tr_b16 v[46:47], v73 offset:16896
	v_permlane32_swap_b32_e32 v34, v36
	v_permlane32_swap_b32_e32 v35, v37
	v_permlane32_swap_b32_e32 v38, v40
	s_waitcnt lgkmcnt(2)
	v_mfma_f32_32x32x16_bf16 v[16:31], v[42:45], v[34:37], v[16:31]
	ds_read_b64_tr_b16 v[42:43], v73 offset:18432
	ds_read_b64_tr_b16 v[44:45], v73 offset:19456
	ds_read_b64_tr_b16 v[52:53], v73 offset:19968
	ds_read_b64_tr_b16 v[50:51], v73 offset:18944
	v_permlane32_swap_b32_e32 v39, v41
	s_waitcnt lgkmcnt(4)
	v_mfma_f32_32x32x16_bf16 v[0:15], v[46:49], v[34:37], v[0:15]
	s_waitcnt lgkmcnt(2)
	v_mfma_f32_32x32x16_bf16 v[16:31], v[42:45], v[38:41], v[16:31]
	s_waitcnt lgkmcnt(0)
	v_mfma_f32_32x32x16_bf16 v[0:15], v[50:53], v[38:41], v[0:15]
	v_add_f32_e32 v33, v133, v72
	v_cmp_gt_u32_e32 vcc, 32, v98
	s_and_saveexec_b64 s[2:3], vcc
	s_cbranch_execz .LBB0_857
	v_log_f32_e32 v34, v33
	s_lshl_b64 s[4:5], s[14:15], 20
	s_add_u32 s4, s13, s4
	s_addc_u32 s5, s38, s5
	v_add_f32_e32 v32, v32, v34
	v_lshlrev_b64 v[34:35], 5, v[94:95]
	v_lshl_add_u64 v[34:35], s[4:5], 0, v[34:35]
	s_lshl_b32 s8, s48, 2
	v_mul_f32_e32 v32, 0x3f317218, v32
	v_lshl_add_u64 v[34:35], v[34:35], 0, s[8:9]
	global_store_dword v[34:35], v32, off
	s_branch .LBB0_857

; DI void finishSM(f32x16& p0, f32x16& p1, float alpha, float& l_reg, bf16x8& pa0, bf16x8& pa1, bf16x8& pa2, bf16x8& pa3) {
; #pragma unroll
;   for (int r = 0; r < 16; ++r) p1[r] = __builtin_amdgcn_exp2f(p1[r]);
;   float ps = 0;
; #pragma unroll
;   for (int r = 0; r < 16; ++r) ps += p0[r];
; #pragma unroll
;   for (int r = 0; r < 16; ++r) ps += p1[r];
;   { auto rr = __builtin_amdgcn_permlane32_swap(__float_as_uint(ps), __float_as_uint(ps), false, false);
;     ps = __uint_as_float(rr[0]) + __uint_as_float(rr[1]); }
;   l_reg = l_reg * alpha + ps;
;   PK4(p0, 0, pa0); PK4(p0, 8, pa1); PK4(p1, 0, pa2); PK4(p1, 8, pa3);
; }
; template <int NPE>
; DI void qkt_r(f32x16& p0, f32x16& p1, const char* Ks, const char* Ps, const bf16x8* qr, int r32, int hi) {
;   p0 = f32x16{}; p1 = f32x16{};
; #pragma unroll
;   for (int d0 = 0; d0 < 8; ++d0) { int cb = (d0 * 16 + hi * 8) * 2;
;     bf16x8 b0 = *reinterpret_cast<const bf16x8*>(Ks + KSWZ(r32, cb));
;     bf16x8 b1 = *reinterpret_cast<const bf16x8*>(Ks + KSWZ(32 + r32, cb));
;     p0 = __builtin_amdgcn_mfma_f32_32x32x16_bf16(b0, qr[d0], p0, 0, 0, 0);
;     p1 = __builtin_amdgcn_mfma_f32_32x32x16_bf16(b1, qr[d0], p1, 0, 0, 0); }
; #pragma unroll
;   for (int d0 = 0; d0 < NPE; ++d0) { int cb = (d0 * 16 + hi * 8) * 2;
;     bf16x8 b0 = *reinterpret_cast<const bf16x8*>(Ps + PSWZ(r32, cb));
;     bf16x8 b1 = *reinterpret_cast<const bf16x8*>(Ps + PSWZ(32 + r32, cb));
;     p0 = __builtin_amdgcn_mfma_f32_32x32x16_bf16(b0, qr[8 + d0], p0, 0, 0, 0);
;     p1 = __builtin_amdgcn_mfma_f32_32x32x16_bf16(b1, qr[8 + d0], p1, 0, 0, 0); }
; }
.LBB0_928:
	s_mov_b32 s63, s1
	v_exp_f32_e32 v160, v185
	v_add_u32_e32 v68, s63, v188
	v_add_u32_e32 v243, s63, v191
	ds_read_b128 v[64:67], v68 offset:16384
	ds_read_b128 v[244:247], v243 offset:16384
	v_add_u32_e32 v252, s63, v194
	v_add_u32_e32 v253, s63, v197
	ds_read_b128 v[226:229], v252 offset:16384
	v_add_u32_e32 v144, s63, v200
	ds_read_b128 v[68:71], v68 offset:24576
	ds_read_b128 v[248:251], v243 offset:24576
	v_add_u32_e32 v243, s63, v203
	ds_read_b128 v[230:233], v252 offset:24576
	v_add_u32_e32 v252, s63, v205
	v_exp_f32_e32 v182, v182
	v_exp_f32_e32 v183, v183
	v_exp_f32_e32 v180, v180
	v_exp_f32_e32 v181, v181
	v_exp_f32_e32 v178, v178
	v_exp_f32_e32 v179, v179
	s_mov_b32 s1, s2
	v_exp_f32_e32 v185, v177
	v_cvt_pk_bf16_f32 v177, v162, v164
	v_exp_f32_e32 v215, v175
	v_cvt_pk_bf16_f32 v175, v166, v168
	v_exp_f32_e32 v186, v174
	v_exp_f32_e32 v216, v172
	v_exp_f32_e32 v225, v173
	v_cvt_pk_bf16_f32 v172, v219, v221
	v_cvt_pk_bf16_f32 v173, v217, v218
	v_cvt_pk_bf16_f32 v174, v167, v169
	v_permlane32_swap_b32_e32 v175, v177
	s_waitcnt lgkmcnt(5)
	v_mfma_f32_32x32x16_bf16 v[80:95], v[64:67], v[136:139], 0
	s_waitcnt lgkmcnt(4)
	v_mfma_f32_32x32x16_bf16 v[80:95], v[244:247], v[132:135], v[80:95]
	s_waitcnt lgkmcnt(3)
	v_mfma_f32_32x32x16_bf16 v[80:95], v[226:229], v[128:131], v[80:95]
	ds_read_b128 v[244:247], v253 offset:16384
	s_waitcnt lgkmcnt(3)
	v_mfma_f32_32x32x16_bf16 v[64:79], v[68:71], v[136:139], 0
	ds_read_b128 v[226:229], v144 offset:16384
	s_waitcnt lgkmcnt(3)
	v_mfma_f32_32x32x16_bf16 v[64:79], v[248:251], v[132:135], v[64:79]
	s_waitcnt lgkmcnt(2)
	v_mfma_f32_32x32x16_bf16 v[64:79], v[230:233], v[128:131], v[64:79]
	ds_read_b128 v[248:251], v253 offset:24576
	v_add_u32_e32 v253, s63, v206
	ds_read_b128 v[230:233], v144 offset:24576
	v_add_u32_e32 v144, s63, v207
	s_waitcnt lgkmcnt(3)
	v_mfma_f32_32x32x16_bf16 v[80:95], v[244:247], v[124:127], v[80:95]
	s_waitcnt lgkmcnt(2)
	v_mfma_f32_32x32x16_bf16 v[80:95], v[226:229], v[120:123], v[80:95]
	ds_read_b128 v[244:247], v243 offset:16384
	ds_read_b128 v[226:229], v252 offset:16384
	s_waitcnt lgkmcnt(3)
	v_mfma_f32_32x32x16_bf16 v[64:79], v[248:251], v[124:127], v[64:79]
	s_waitcnt lgkmcnt(2)
	v_mfma_f32_32x32x16_bf16 v[64:79], v[230:233], v[120:123], v[64:79]
	ds_read_b128 v[248:251], v243 offset:24576
	v_add_u32_e32 v243, s63, v208
	ds_read_b128 v[230:233], v252 offset:24576
	v_add_u32_e32 v252, s63, v209
	s_waitcnt lgkmcnt(3)
	v_mfma_f32_32x32x16_bf16 v[80:95], v[244:247], v[112:115], v[80:95]
	s_waitcnt lgkmcnt(2)
	v_mfma_f32_32x32x16_bf16 v[80:95], v[226:229], v[108:111], v[80:95]
	ds_read_b128 v[244:247], v253 offset:16384
	ds_read_b128 v[226:229], v144 offset:32768
	s_waitcnt lgkmcnt(3)
	v_mfma_f32_32x32x16_bf16 v[64:79], v[248:251], v[112:115], v[64:79]
	s_waitcnt lgkmcnt(2)
	v_mfma_f32_32x32x16_bf16 v[64:79], v[230:233], v[108:111], v[64:79]
	ds_read_b128 v[248:251], v253 offset:24576
	v_add_u32_e32 v253, s63, v210
	ds_read_b128 v[230:233], v144 offset:36864
	v_exp_f32_e32 v144, v184
	v_exp_f32_e32 v184, v176
	v_cvt_pk_bf16_f32 v176, v163, v165
	s_waitcnt lgkmcnt(3)
	v_mfma_f32_32x32x16_bf16 v[80:95], v[244:247], v[100:103], v[80:95]
	s_waitcnt lgkmcnt(2)
	v_mfma_f32_32x32x16_bf16 v[80:95], v[226:229], v[104:107], v[80:95]
	ds_read_b128 v[244:247], v243 offset:32768
	v_permlane32_swap_b32_e32 v174, v176
	ds_read_b128 v[226:229], v252 offset:32768
	s_waitcnt lgkmcnt(3)
	v_mfma_f32_32x32x16_bf16 v[64:79], v[248:251], v[100:103], v[64:79]
	s_waitcnt lgkmcnt(2)
	v_mfma_f32_32x32x16_bf16 v[64:79], v[230:233], v[104:107], v[64:79]
	ds_read_b128 v[248:251], v243 offset:36864
	v_add_u32_e32 v243, s1, v147
	ds_read_b128 v[230:233], v252 offset:36864
	s_waitcnt lgkmcnt(3)
	v_mfma_f32_32x32x16_bf16 v[80:95], v[244:247], v[140:143], v[80:95]
	s_waitcnt lgkmcnt(2)
	v_mfma_f32_32x32x16_bf16 v[80:95], v[226:229], v[96:99], v[80:95]
	ds_read_b128 v[244:247], v253 offset:32768
	v_exp_f32_e32 v226, v170
	v_add_f32_e32 v170, 0, v222
	v_exp_f32_e32 v227, v171
	v_add_f32_e32 v170, v224, v170
	v_cvt_pk_bf16_f32 v171, v220, v223
	v_add_f32_e32 v170, v220, v170
	s_waitcnt lgkmcnt(2)
	v_mfma_f32_32x32x16_bf16 v[64:79], v[248:251], v[140:143], v[64:79]
	v_add_f32_e32 v170, v223, v170
	v_permlane32_swap_b32_e32 v171, v173
	v_add_f32_e32 v170, v219, v170
	v_add_f32_e32 v170, v221, v170
	ds_read_b64_tr_b16 v[220:221], v243 offset:0x3000
	s_waitcnt lgkmcnt(2)
	v_mfma_f32_32x32x16_bf16 v[64:79], v[230:233], v[96:99], v[64:79]
	v_add_f32_e32 v170, v217, v170
	v_add_f32_e32 v170, v218, v170
	ds_read_b64_tr_b16 v[218:219], v243 offset:0x2800
	v_add_f32_e32 v170, v167, v170
	v_cvt_pk_bf16_f32 v167, v186, v215
	v_add_f32_e32 v170, v169, v170
	v_cvt_pk_bf16_f32 v169, v226, v227
	v_add_f32_e32 v170, v166, v170
	v_cvt_pk_bf16_f32 v166, v184, v185
	v_add_f32_e32 v170, v168, v170
	v_cvt_pk_bf16_f32 v168, v216, v225
	v_add_f32_e32 v170, v163, v170
	v_cvt_pk_bf16_f32 v163, v182, v183
	v_add_f32_e32 v170, v165, v170
	v_cvt_pk_bf16_f32 v165, v178, v179
	v_add_f32_e32 v170, v162, v170
	v_cvt_pk_bf16_f32 v162, v144, v160
	v_add_f32_e32 v170, v164, v170
	v_cvt_pk_bf16_f32 v164, v180, v181
	v_add_f32_e32 v170, v144, v170
	v_permlane32_swap_b32_e32 v163, v165
	v_add_f32_e32 v170, v160, v170
	v_permlane32_swap_b32_e32 v162, v164
	v_add_f32_e32 v170, v182, v170
	ds_read_b128 v[230:233], v253 offset:36864
	v_add_f32_e32 v170, v183, v170
	ds_read_b64_tr_b16 v[182:183], v243 offset:0x1000
	v_add_f32_e32 v170, v180, v170
	v_permlane32_swap_b32_e32 v166, v168
	v_add_f32_e32 v170, v181, v170
	ds_read_b64_tr_b16 v[180:181], v243 offset:0x800
	v_add_f32_e32 v170, v178, v170
	v_permlane32_swap_b32_e32 v167, v169
	v_add_f32_e32 v170, v179, v170
	ds_read_b64_tr_b16 v[178:179], v243 offset:0
	v_add_f32_e32 v170, v184, v170
	v_add_f32_e32 v170, v185, v170
	ds_read_b64_tr_b16 v[184:185], v243 offset:0x1800
	v_add_f32_e32 v170, v186, v170
	s_waitcnt lgkmcnt(7)
; #define SBAR() __builtin_amdgcn_sched_barrier(0)
; DI void partialSM(f32x16& p0, f32x16& p1, float& m_reg, float& mn, float& alpha, const float SCALE) {
;   const float C = SCALE * 1.4426950408889634f;
;   float pmax = p0[0];
; #pragma unroll
;   for (int r = 1; r < 16; ++r) pmax = fmaxf(pmax, p0[r]);
; #pragma unroll
;   for (int r = 0; r < 16; ++r) pmax = fmaxf(pmax, p1[r]);
;   { auto rr = __builtin_amdgcn_permlane32_swap(__float_as_uint(pmax), __float_as_uint(pmax), false, false);
;     pmax = fmaxf(__uint_as_float(rr[0]), __uint_as_float(rr[1])); }
;   if (__builtin_expect(__all(pmax - m_reg <= THR / SCALE), 1)) { mn = m_reg; alpha = 1.f; }
;   else { mn = fmaxf(m_reg, pmax); alpha = __builtin_amdgcn_exp2f((m_reg - mn) * C); m_reg = mn; }
; template <int D0, bool SPLIT> DI void pv_one(f32x16& od, int vb, bf16x8 pa0, bf16x8 pa1, bf16x8 pa2, bf16x8 pa3) {
;     ...
;   const s16x4 l0 = tr_read<v_rd_off(D0, 0, 0)>(vb), h0 = tr_read<v_rd_off(D0, 0, 1)>(vb), l1 = tr_read<v_rd_off(D0, 1, 0)>(vb), h1 = tr_read<v_rd_off(D0, 1, 1)>(vb);
;   const s16x4 l2 = tr_read<v_rd_off(D0, 2, 0)>(vb), h2 = tr_read<v_rd_off(D0, 2, 1)>(vb), l3 = tr_read<v_rd_off(D0, 3, 0)>(vb), h3 = tr_read<v_rd_off(D0, 3, 1)>(vb);
;   asm volatile("s_waitcnt lgkmcnt(0)" ::: "memory"); SBAR();
;   od = __builtin_amdgcn_mfma_f32_32x32x16_bf16(PKV(l0, h0), pa0, od, 0, 0, 0);
;   od = __builtin_amdgcn_mfma_f32_32x32x16_bf16(PKV(l1, h1), pa1, od, 0, 0, 0);
;   od = __builtin_amdgcn_mfma_f32_32x32x16_bf16(PKV(l2, h2), pa2, od, 0, 0, 0);
;   od = __builtin_amdgcn_mfma_f32_32x32x16_bf16(PKV(l3, h3), pa3, od, 0, 0, 0);
	v_mfma_f32_32x32x16_bf16 v[80:95], v[244:247], v[116:119], v[80:95]
	v_add_f32_e32 v170, v215, v170
	v_add_f32_e32 v170, v216, v170
	ds_read_b64_tr_b16 v[216:217], v243 offset:0x2000
	v_add_f32_e32 v170, v225, v170
	v_add_f32_e32 v170, v226, v170
	v_add_f32_e32 v213, v227, v170
	v_cvt_pk_bf16_f32 v170, v222, v224
	ds_read_b64_tr_b16 v[222:223], v243 offset:0x3800
	ds_read_b64_tr_b16 v[224:225], v243 offset:0x3200
	ds_read_b64_tr_b16 v[226:227], v243 offset:0x3a00
	v_permlane32_swap_b32_e32 v170, v172
	v_mov_b32_e32 v214, v213
	v_max_f32_e32 v252, v81, v81
	v_max_f32_e32 v160, v80, v80
	v_permlane32_swap_b32_e32 v213, v214
	v_max_f32_e32 v252, v160, v252
	v_max3_f32 v252, v252, v82, v83
	v_max3_f32 v252, v252, v84, v85
	v_max3_f32 v252, v252, v86, v87
	v_max3_f32 v252, v252, v88, v89
	v_max3_f32 v252, v252, v90, v91
	v_max3_f32 v252, v252, v92, v93
	v_max3_f32 v252, v252, v94, v95
	s_waitcnt lgkmcnt(8)
	v_mfma_f32_32x32x16_bf16 v[64:79], v[230:233], v[116:119], v[64:79]
	s_waitcnt lgkmcnt(5)
	v_mfma_f32_32x32x16_bf16 v[16:31], v[178:181], v[170:173], v[16:31]
	s_waitcnt lgkmcnt(4)
	v_mfma_f32_32x32x16_bf16 v[16:31], v[182:185], v[174:177], v[16:31]
	ds_read_b64_tr_b16 v[178:179], v243 offset:0x200
	ds_read_b64_tr_b16 v[180:181], v243 offset:0xa00
	s_waitcnt lgkmcnt(5)
	v_mfma_f32_32x32x16_bf16 v[16:31], v[216:219], v[162:165], v[16:31]
	ds_read_b64_tr_b16 v[182:183], v243 offset:0x1200
	ds_read_b64_tr_b16 v[184:185], v243 offset:0x1a00
	s_waitcnt lgkmcnt(6)
	v_mfma_f32_32x32x16_bf16 v[16:31], v[220:223], v[166:169], v[16:31]
	ds_read_b64_tr_b16 v[216:217], v243 offset:0x2200
	ds_read_b64_tr_b16 v[218:219], v243 offset:0x2a00
	ds_read_b64_tr_b16 v[220:221], v243 offset:0x3400
	ds_read_b64_tr_b16 v[222:223], v243 offset:0x3c00
	v_max3_f32 v252, v252, v64, v65
	v_max3_f32 v252, v252, v66, v67
	v_max3_f32 v252, v252, v68, v69
	v_max3_f32 v252, v252, v70, v71
	v_max3_f32 v252, v252, v72, v73
	v_max3_f32 v252, v252, v74, v75
	v_max3_f32 v252, v252, v76, v77
	v_max3_f32 v252, v252, v78, v79
	v_mov_b32_e32 v160, v252
	s_waitcnt lgkmcnt(6)
	v_mfma_f32_32x32x16_bf16 v[48:63], v[178:181], v[170:173], v[48:63]
	s_waitcnt lgkmcnt(4)
	v_mfma_f32_32x32x16_bf16 v[48:63], v[182:185], v[174:177], v[48:63]
	ds_read_b64_tr_b16 v[178:179], v243 offset:0x400
	ds_read_b64_tr_b16 v[180:181], v243 offset:0xc00
	v_permlane32_swap_b32_e32 v252, v160
	v_max_f32_e32 v160, v160, v160
	v_max_f32_e32 v252, v252, v252
	s_waitcnt lgkmcnt(4)
	v_mfma_f32_32x32x16_bf16 v[48:63], v[216:219], v[162:165], v[48:63]
	ds_read_b64_tr_b16 v[182:183], v243 offset:0x1400
	ds_read_b64_tr_b16 v[184:185], v243 offset:0x1c00
	v_max_f32_e32 v252, v252, v160
	v_max_f32_e32 v160, v212, v212
	v_max_f32_e32 v160, v160, v252
	v_mfma_f32_32x32x16_bf16 v[48:63], v[224:227], v[166:169], v[48:63]
	ds_read_b64_tr_b16 v[216:217], v243 offset:0x2400
	ds_read_b64_tr_b16 v[218:219], v243 offset:0x2c00
	v_sub_f32_e32 v144, v212, v160
	v_mul_f32_e32 v144, 0x3dd53b94, v144
	ds_read_b64_tr_b16 v[224:225], v243 offset:0x3600
	ds_read_b64_tr_b16 v[226:227], v243 offset:0x3e00
	v_exp_f32_e32 v144, v144
	s_waitcnt lgkmcnt(6)
	v_mfma_f32_32x32x16_bf16 v[32:47], v[178:181], v[170:173], v[32:47]
	s_waitcnt lgkmcnt(4)
	v_mfma_f32_32x32x16_bf16 v[32:47], v[182:185], v[174:177], v[32:47]
	ds_read_b64_tr_b16 v[178:179], v243 offset:0x600
	ds_read_b64_tr_b16 v[180:181], v243 offset:0xe00
	s_waitcnt lgkmcnt(4)
	v_mfma_f32_32x32x16_bf16 v[32:47], v[216:219], v[162:165], v[32:47]
	ds_read_b64_tr_b16 v[182:183], v243 offset:0x1600
	ds_read_b64_tr_b16 v[184:185], v243 offset:0x1e00
	v_mfma_f32_32x32x16_bf16 v[32:47], v[220:223], v[166:169], v[32:47]
	ds_read_b64_tr_b16 v[216:217], v243 offset:0x2600
	ds_read_b64_tr_b16 v[218:219], v243 offset:0x2e00
	s_waitcnt lgkmcnt(4)
	v_mfma_f32_32x32x16_bf16 v[0:15], v[178:181], v[170:173], v[0:15]
	s_waitcnt lgkmcnt(2)
	v_mfma_f32_32x32x16_bf16 v[0:15], v[182:185], v[174:177], v[0:15]
	s_waitcnt lgkmcnt(0)
	v_mfma_f32_32x32x16_bf16 v[0:15], v[216:219], v[162:165], v[0:15]
	v_mfma_f32_32x32x16_bf16 v[0:15], v[224:227], v[166:169], v[0:15]
	v_sub_f32_e32 v162, v252, v212
	v_cmp_ge_f32_e32 vcc, s91, v162
	s_cmp_eq_u64 vcc, exec
	s_cselect_b64 s[2:3], -1, 0
	v_cndmask_b32_e64 v144, v144, 1.0, s[2:3]
	s_cbranch_scc1 .LBB0_930
	v_pk_mul_f32 v[30:31], v[30:31], v[144:145] op_sel_hi:[1,0]
	v_pk_mul_f32 v[28:29], v[28:29], v[144:145] op_sel_hi:[1,0]
	v_pk_mul_f32 v[26:27], v[26:27], v[144:145] op_sel_hi:[1,0]
	v_pk_mul_f32 v[24:25], v[24:25], v[144:145] op_sel_hi:[1,0]
	v_pk_mul_f32 v[22:23], v[22:23], v[144:145] op_sel_hi:[1,0]
	v_pk_mul_f32 v[20:21], v[20:21], v[144:145] op_sel_hi:[1,0]
	v_pk_mul_f32 v[18:19], v[18:19], v[144:145] op_sel_hi:[1,0]
	v_pk_mul_f32 v[16:17], v[16:17], v[144:145] op_sel_hi:[1,0]
	v_pk_mul_f32 v[62:63], v[62:63], v[144:145] op_sel_hi:[1,0]
	v_pk_mul_f32 v[60:61], v[60:61], v[144:145] op_sel_hi:[1,0]
	v_pk_mul_f32 v[58:59], v[58:59], v[144:145] op_sel_hi:[1,0]
	v_pk_mul_f32 v[56:57], v[56:57], v[144:145] op_sel_hi:[1,0]
	v_pk_mul_f32 v[54:55], v[54:55], v[144:145] op_sel_hi:[1,0]
	v_pk_mul_f32 v[52:53], v[52:53], v[144:145] op_sel_hi:[1,0]
	v_pk_mul_f32 v[50:51], v[50:51], v[144:145] op_sel_hi:[1,0]
	v_pk_mul_f32 v[48:49], v[48:49], v[144:145] op_sel_hi:[1,0]
	v_pk_mul_f32 v[46:47], v[46:47], v[144:145] op_sel_hi:[1,0]
	v_pk_mul_f32 v[44:45], v[44:45], v[144:145] op_sel_hi:[1,0]
	v_pk_mul_f32 v[42:43], v[42:43], v[144:145] op_sel_hi:[1,0]
	v_pk_mul_f32 v[40:41], v[40:41], v[144:145] op_sel_hi:[1,0]
	v_pk_mul_f32 v[38:39], v[38:39], v[144:145] op_sel_hi:[1,0]
	v_pk_mul_f32 v[36:37], v[36:37], v[144:145] op_sel_hi:[1,0]
	v_pk_mul_f32 v[34:35], v[34:35], v[144:145] op_sel_hi:[1,0]
	v_pk_mul_f32 v[32:33], v[32:33], v[144:145] op_sel_hi:[1,0]
	v_pk_mul_f32 v[14:15], v[14:15], v[144:145] op_sel_hi:[1,0]
	v_pk_mul_f32 v[12:13], v[12:13], v[144:145] op_sel_hi:[1,0]
	v_pk_mul_f32 v[10:11], v[10:11], v[144:145] op_sel_hi:[1,0]
	v_pk_mul_f32 v[8:9], v[8:9], v[144:145] op_sel_hi:[1,0]
	v_pk_mul_f32 v[6:7], v[6:7], v[144:145] op_sel_hi:[1,0]
	v_pk_mul_f32 v[4:5], v[4:5], v[144:145] op_sel_hi:[1,0]
	v_pk_mul_f32 v[2:3], v[2:3], v[144:145] op_sel_hi:[1,0]
	v_pk_mul_f32 v[0:1], v[0:1], v[144:145] op_sel_hi:[1,0]
; DI void partialSM(f32x16& p0, f32x16& p1, float& m_reg, float& mn, float& alpha, const float SCALE) {
;     ...
;   float mnC = -mn * C;
; #pragma unroll
;   for (int r = 0; r < 16; ++r) p0[r] = fmaf(p0[r], C, mnC);
; #pragma unroll
;   for (int r = 0; r < 16; ++r) p1[r] = fmaf(p1[r], C, mnC);
; #pragma unroll
;   for (int r = 0; r < 16; ++r) p0[r] = __builtin_amdgcn_exp2f(p0[r]);
; template <int NPE>
; DI void qkt_r(f32x16& p0, f32x16& p1, const char* Ks, const char* Ps, const bf16x8* qr, int r32, int hi) {
;   p0 = f32x16{}; p1 = f32x16{};
; #pragma unroll
;   for (int d0 = 0; d0 < 8; ++d0) { int cb = (d0 * 16 + hi * 8) * 2;
;     bf16x8 b0 = *reinterpret_cast<const bf16x8*>(Ks + KSWZ(r32, cb));
;     bf16x8 b1 = *reinterpret_cast<const bf16x8*>(Ks + KSWZ(32 + r32, cb));
;     p0 = __builtin_amdgcn_mfma_f32_32x32x16_bf16(b0, qr[d0], p0, 0, 0, 0);
;     p1 = __builtin_amdgcn_mfma_f32_32x32x16_bf16(b1, qr[d0], p1, 0, 0, 0); }
; #pragma unroll
;   for (int d0 = 0; d0 < NPE; ++d0) { int cb = (d0 * 16 + hi * 8) * 2;
;     bf16x8 b0 = *reinterpret_cast<const bf16x8*>(Ps + PSWZ(r32, cb));
;     bf16x8 b1 = *reinterpret_cast<const bf16x8*>(Ps + PSWZ(32 + r32, cb));
;     p0 = __builtin_amdgcn_mfma_f32_32x32x16_bf16(b0, qr[8 + d0], p0, 0, 0, 0);
;     p1 = __builtin_amdgcn_mfma_f32_32x32x16_bf16(b1, qr[8 + d0], p1, 0, 0, 0); }
; }
.LBB0_930:
	v_add_u32_e32 v168, s1, v148
	s_add_i32 s30, s1, 0x4000
	v_lshl_add_u64 v[162:163], v[154:155], 0, s[4:5]
	v_readfirstlane_b32 s31, v168
	v_add_u32_e32 v170, s30, v148
	v_lshl_add_u64 v[164:165], v[162:163], 0, s[38:39]
	v_readfirstlane_b32 s30, v170
	s_mov_b32 m0, s31
	s_waitcnt vmcnt(0) lgkmcnt(0)
	v_add_u32_e32 v168, 0x400, v168
	s_barrier
	global_load_lds_dwordx4 v[164:165], off
	v_lshl_add_u64 v[164:165], v[156:157], 0, s[4:5]
	s_mov_b32 m0, s30
	v_readfirstlane_b32 s30, v168
	v_lshl_add_u64 v[166:167], v[164:165], 0, s[40:41]
	v_add_u32_e32 v170, 0x400, v170
	global_load_lds_dwordx4 v[166:167], off
	s_mov_b32 m0, s30
	v_readfirstlane_b32 s30, v170
	v_lshl_add_u64 v[166:167], v[162:163], 0, s[42:43]
	v_add_u32_e32 v243, s62, v191
	global_load_lds_dwordx4 v[166:167], off
	v_lshl_add_u64 v[166:167], v[158:159], 0, s[4:5]
	s_mov_b32 m0, s30
	s_add_i32 s30, s1, 0x8000
	v_lshl_add_u64 v[168:169], v[166:167], 0, s[40:41]
	v_add_u32_e32 v172, s30, v150
	global_load_lds_dwordx4 v[168:169], off
	v_readfirstlane_b32 s30, v172
	v_lshl_add_u64 v[168:169], v[152:153], 0, s[4:5]
	ds_read_b128 v[176:179], v243 offset:24576
	v_lshl_add_u64 v[170:171], v[168:169], 0, s[44:45]
	s_mov_b32 m0, s30
	v_add_u32_e32 v252, s62, v194
	global_load_lds_dwordx4 v[170:171], off
	v_cndmask_b32_e64 v170, v160, v212, s[2:3]
	v_add_u32_e32 v253, s62, v197
	v_mul_f32_e32 v160, 0xbdd53b94, v170
	ds_read_b128 v[244:247], v243 offset:16384
	v_fmamk_f32 v80, v80, 0x3dd53b94, v160
	v_fmamk_f32 v81, v81, 0x3dd53b94, v160
	v_fmamk_f32 v82, v82, 0x3dd53b94, v160
	v_fmamk_f32 v83, v83, 0x3dd53b94, v160
	v_fmamk_f32 v183, v68, 0x3dd53b94, v160
	v_add_u32_e32 v68, s62, v188
	v_exp_f32_e32 v219, v80
	v_exp_f32_e32 v220, v81
	v_exp_f32_e32 v221, v82
	v_exp_f32_e32 v222, v83
	ds_read_b128 v[80:83], v68 offset:24576
	v_fmamk_f32 v84, v84, 0x3dd53b94, v160
	v_fmamk_f32 v85, v85, 0x3dd53b94, v160
	v_fmamk_f32 v86, v86, 0x3dd53b94, v160
	v_fmamk_f32 v87, v87, 0x3dd53b94, v160
	v_fmamk_f32 v88, v88, 0x3dd53b94, v160
	v_fmamk_f32 v89, v89, 0x3dd53b94, v160
	v_fmamk_f32 v90, v90, 0x3dd53b94, v160
	v_fmamk_f32 v91, v91, 0x3dd53b94, v160
	v_fmamk_f32 v92, v92, 0x3dd53b94, v160
	v_fmamk_f32 v93, v93, 0x3dd53b94, v160
	v_fmamk_f32 v94, v94, 0x3dd53b94, v160
	v_fmamk_f32 v95, v95, 0x3dd53b94, v160
	v_exp_f32_e32 v223, v84
	v_exp_f32_e32 v224, v85
	v_exp_f32_e32 v225, v86
	v_exp_f32_e32 v226, v87
	v_exp_f32_e32 v227, v88
	v_exp_f32_e32 v228, v89
	v_exp_f32_e32 v229, v90
	v_exp_f32_e32 v230, v91
	v_exp_f32_e32 v231, v92
	v_exp_f32_e32 v232, v93
	v_exp_f32_e32 v233, v94
	v_exp_f32_e32 v234, v95
	v_fmamk_f32 v171, v64, 0x3dd53b94, v160
	v_fmamk_f32 v180, v65, 0x3dd53b94, v160
	v_fmamk_f32 v181, v66, 0x3dd53b94, v160
	v_fmamk_f32 v182, v67, 0x3dd53b94, v160
	ds_read_b128 v[64:67], v68 offset:16384
	v_fmamk_f32 v184, v69, 0x3dd53b94, v160
	v_fmamk_f32 v185, v70, 0x3dd53b94, v160
	v_fmamk_f32 v186, v71, 0x3dd53b94, v160
	v_fmamk_f32 v212, v72, 0x3dd53b94, v160
	v_fmamk_f32 v215, v73, 0x3dd53b94, v160
	v_fmamk_f32 v216, v74, 0x3dd53b94, v160
	v_fmamk_f32 v217, v75, 0x3dd53b94, v160
	v_fmamk_f32 v218, v76, 0x3dd53b94, v160
	v_fmamk_f32 v235, v77, 0x3dd53b94, v160
	v_fmamk_f32 v236, v78, 0x3dd53b94, v160
	v_fmac_f32_e32 v160, 0x3dd53b94, v79
	v_add_u32_e32 v243, s62, v203
	ds_read_b128 v[248:251], v252 offset:16384
	ds_read_b128 v[172:175], v253 offset:16384
	v_exp_f32_e32 v171, v171
	v_exp_f32_e32 v180, v180
	v_exp_f32_e32 v181, v181
	v_exp_f32_e32 v182, v182
	s_waitcnt lgkmcnt(3)
	v_mfma_f32_32x32x16_bf16 v[80:95], v[80:83], v[136:139], 0
	v_exp_f32_e32 v183, v183
	v_exp_f32_e32 v184, v184
	v_exp_f32_e32 v185, v185
	v_mfma_f32_32x32x16_bf16 v[80:95], v[176:179], v[132:135], v[80:95]
	v_exp_f32_e32 v186, v186
	v_exp_f32_e32 v212, v212
	v_exp_f32_e32 v237, v215
	ds_read_b128 v[176:179], v252 offset:24576
	v_add_u32_e32 v252, s62, v205
	v_exp_f32_e32 v238, v216
	v_exp_f32_e32 v217, v217
	v_exp_f32_e32 v239, v218
	v_exp_f32_e32 v235, v235
	v_exp_f32_e32 v236, v236
	v_exp_f32_e32 v160, v160
	v_cvt_pk_bf16_f32 v218, v212, v237
	s_waitcnt lgkmcnt(3)
	v_mfma_f32_32x32x16_bf16 v[64:79], v[64:67], v[136:139], 0
	v_mfma_f32_32x32x16_bf16 v[64:79], v[244:247], v[132:135], v[64:79]
	s_waitcnt lgkmcnt(2)
	v_mfma_f32_32x32x16_bf16 v[64:79], v[248:251], v[128:131], v[64:79]
	s_waitcnt lgkmcnt(1)
	v_mfma_f32_32x32x16_bf16 v[64:79], v[172:175], v[124:127], v[64:79]
	ds_read_b128 v[248:251], v243 offset:16384
	ds_read_b128 v[172:175], v252 offset:16384
	s_waitcnt lgkmcnt(2)
	v_mfma_f32_32x32x16_bf16 v[80:95], v[176:179], v[128:131], v[80:95]
	ds_read_b128 v[176:179], v253 offset:24576
	v_add_u32_e32 v253, s62, v206
	s_waitcnt lgkmcnt(0)
	v_mfma_f32_32x32x16_bf16 v[80:95], v[176:179], v[124:127], v[80:95]
	v_add_u32_e32 v176, s62, v200
	ds_read_b128 v[244:247], v176 offset:16384
	ds_read_b128 v[176:179], v176 offset:24576
	s_waitcnt lgkmcnt(1)
	v_mfma_f32_32x32x16_bf16 v[64:79], v[244:247], v[120:123], v[64:79]
	s_waitcnt lgkmcnt(0)
	v_mfma_f32_32x32x16_bf16 v[80:95], v[176:179], v[120:123], v[80:95]
	ds_read_b128 v[244:247], v253 offset:16384
	v_mfma_f32_32x32x16_bf16 v[64:79], v[248:251], v[112:115], v[64:79]
	ds_read_b128 v[176:179], v243 offset:24576
	v_add_u32_e32 v243, s62, v208
	v_mfma_f32_32x32x16_bf16 v[64:79], v[172:175], v[108:111], v[64:79]
	ds_read_b128 v[172:175], v243 offset:32768
	s_waitcnt lgkmcnt(2)
	v_mfma_f32_32x32x16_bf16 v[64:79], v[244:247], v[100:103], v[64:79]
	s_waitcnt lgkmcnt(1)
	v_mfma_f32_32x32x16_bf16 v[80:95], v[176:179], v[112:115], v[80:95]
	ds_read_b128 v[176:179], v252 offset:24576
	v_add_u32_e32 v252, s62, v209
	ds_read_b128 v[244:247], v252 offset:32768
	s_waitcnt lgkmcnt(1)
; #define SBAR() __builtin_amdgcn_sched_barrier(0)
; DI void finishSM(f32x16& p0, f32x16& p1, float alpha, float& l_reg, bf16x8& pa0, bf16x8& pa1, bf16x8& pa2, bf16x8& pa3) {
; #pragma unroll
;   for (int r = 0; r < 16; ++r) p1[r] = __builtin_amdgcn_exp2f(p1[r]);
;   float ps = 0;
; #pragma unroll
;   for (int r = 0; r < 16; ++r) ps += p0[r];
; #pragma unroll
;   for (int r = 0; r < 16; ++r) ps += p1[r];
;   { auto rr = __builtin_amdgcn_permlane32_swap(__float_as_uint(ps), __float_as_uint(ps), false, false);
;     ps = __uint_as_float(rr[0]) + __uint_as_float(rr[1]); }
;   l_reg = l_reg * alpha + ps;
;   PK4(p0, 0, pa0); PK4(p0, 8, pa1); PK4(p1, 0, pa2); PK4(p1, 8, pa3);
; }
; template <int D0, bool SPLIT> DI void pv_one(f32x16& od, int vb, bf16x8 pa0, bf16x8 pa1, bf16x8 pa2, bf16x8 pa3) {
;     ...
;   const s16x4 l0 = tr_read<v_rd_off(D0, 0, 0)>(vb), h0 = tr_read<v_rd_off(D0, 0, 1)>(vb), l1 = tr_read<v_rd_off(D0, 1, 0)>(vb), h1 = tr_read<v_rd_off(D0, 1, 1)>(vb);
;   const s16x4 l2 = tr_read<v_rd_off(D0, 2, 0)>(vb), h2 = tr_read<v_rd_off(D0, 2, 1)>(vb), l3 = tr_read<v_rd_off(D0, 3, 0)>(vb), h3 = tr_read<v_rd_off(D0, 3, 1)>(vb);
;   asm volatile("s_waitcnt lgkmcnt(0)" ::: "memory"); SBAR();
;   od = __builtin_amdgcn_mfma_f32_32x32x16_bf16(PKV(l0, h0), pa0, od, 0, 0, 0);
;   od = __builtin_amdgcn_mfma_f32_32x32x16_bf16(PKV(l1, h1), pa1, od, 0, 0, 0);
;   od = __builtin_amdgcn_mfma_f32_32x32x16_bf16(PKV(l2, h2), pa2, od, 0, 0, 0);
;   od = __builtin_amdgcn_mfma_f32_32x32x16_bf16(PKV(l3, h3), pa3, od, 0, 0, 0);
	v_mfma_f32_32x32x16_bf16 v[80:95], v[176:179], v[108:111], v[80:95]
	ds_read_b128 v[176:179], v253 offset:24576
	v_add_u32_e32 v253, s62, v210
	s_waitcnt lgkmcnt(0)
	v_mfma_f32_32x32x16_bf16 v[80:95], v[176:179], v[100:103], v[80:95]
	v_add_u32_e32 v176, s62, v207
	ds_read_b128 v[248:251], v176 offset:32768
	ds_read_b128 v[176:179], v176 offset:36864
	s_waitcnt lgkmcnt(1)
	v_mfma_f32_32x32x16_bf16 v[64:79], v[248:251], v[104:107], v[64:79]
	s_waitcnt lgkmcnt(0)
	v_mfma_f32_32x32x16_bf16 v[80:95], v[176:179], v[104:107], v[80:95]
	ds_read_b128 v[248:251], v253 offset:32768
	v_mfma_f32_32x32x16_bf16 v[64:79], v[172:175], v[140:143], v[64:79]
	ds_read_b128 v[176:179], v243 offset:36864
	v_mfma_f32_32x32x16_bf16 v[64:79], v[244:247], v[96:99], v[64:79]
	v_add_f32_e32 v172, 0, v219
	v_cvt_pk_bf16_f32 v173, v221, v222
	v_add_f32_e32 v172, v220, v172
	v_cvt_pk_bf16_f32 v174, v223, v224
	v_add_f32_e32 v172, v221, v172
	v_cvt_pk_bf16_f32 v221, v236, v160
	v_add_f32_e32 v172, v222, v172
	v_cvt_pk_bf16_f32 v175, v225, v226
	v_add_f32_e32 v172, v223, v172
	v_add_f32_e32 v172, v224, v172
	v_permlane32_swap_b32_e32 v173, v175
	v_add_f32_e32 v172, v225, v172
	v_add_f32_e32 v172, v226, v172
	v_add_f32_e32 v172, v227, v172
	v_add_f32_e32 v172, v228, v172
	v_add_f32_e32 v172, v229, v172
	v_add_f32_e32 v172, v230, v172
	v_add_f32_e32 v172, v231, v172
	v_add_f32_e32 v172, v232, v172
	v_add_f32_e32 v172, v233, v172
	v_add_f32_e32 v172, v234, v172
	v_add_f32_e32 v172, v171, v172
	v_add_f32_e32 v172, v180, v172
	v_cvt_pk_bf16_f32 v180, v171, v180
	v_add_f32_e32 v172, v181, v172
	v_cvt_pk_bf16_f32 v181, v181, v182
	v_add_f32_e32 v172, v182, v172
	v_cvt_pk_bf16_f32 v182, v183, v184
	v_add_f32_e32 v172, v183, v172
	v_cvt_pk_bf16_f32 v183, v185, v186
	v_add_f32_e32 v172, v184, v172
	v_permlane32_swap_b32_e32 v180, v182
	v_add_f32_e32 v172, v185, v172
	v_permlane32_swap_b32_e32 v181, v183
	v_add_f32_e32 v172, v186, v172
	v_add_f32_e32 v172, v212, v172
	s_waitcnt lgkmcnt(1)
	v_mfma_f32_32x32x16_bf16 v[64:79], v[248:251], v[116:119], v[64:79]
	v_add_f32_e32 v172, v237, v172
	v_add_f32_e32 v172, v238, v172
	v_add_f32_e32 v172, v217, v172
	s_waitcnt lgkmcnt(0)
	v_mfma_f32_32x32x16_bf16 v[80:95], v[176:179], v[140:143], v[80:95]
	v_add_f32_e32 v172, v239, v172
	v_add_f32_e32 v172, v235, v172
	v_add_f32_e32 v172, v236, v172
	ds_read_b128 v[176:179], v252 offset:36864
	v_add_f32_e32 v215, v160, v172
	v_add_u32_e32 v160, s63, v147
	v_cvt_pk_bf16_f32 v172, v219, v220
	ds_read_b64_tr_b16 v[222:223], v160 offset:0
	ds_read_b64_tr_b16 v[224:225], v160 offset:0x800
	v_cvt_pk_bf16_f32 v219, v238, v217
	v_permlane32_swap_b32_e32 v172, v174
	v_cvt_pk_bf16_f32 v220, v239, v235
	ds_read_b64_tr_b16 v[236:237], v160 offset:0x3800
	ds_read_b64_tr_b16 v[238:239], v160 offset:0x3200
	ds_read_b64_tr_b16 v[240:241], v160 offset:0x3a00
	v_permlane32_swap_b32_e32 v218, v220
	v_permlane32_swap_b32_e32 v219, v221
	v_max_f32_e32 v171, v64, v64
	v_mov_b32_e32 v216, v215
	s_waitcnt lgkmcnt(5)
	v_mfma_f32_32x32x16_bf16 v[80:95], v[176:179], v[96:99], v[80:95]
	s_waitcnt lgkmcnt(3)
	v_mfma_f32_32x32x16_bf16 v[16:31], v[222:225], v[172:175], v[16:31]
	ds_read_b128 v[176:179], v253 offset:36864
	v_permlane32_swap_b32_e32 v215, v216
	ds_read_b64_tr_b16 v[222:223], v160 offset:0x200
	ds_read_b64_tr_b16 v[224:225], v160 offset:0xa00
	s_waitcnt lgkmcnt(2)
	v_mfma_f32_32x32x16_bf16 v[80:95], v[176:179], v[116:119], v[80:95]
	s_waitcnt lgkmcnt(0)
	v_mfma_f32_32x32x16_bf16 v[48:63], v[222:225], v[172:175], v[48:63]
	v_cvt_pk_bf16_f32 v176, v227, v228
	v_cvt_pk_bf16_f32 v177, v229, v230
	ds_read_b64_tr_b16 v[226:227], v160 offset:0x1000
	ds_read_b64_tr_b16 v[228:229], v160 offset:0x1800
	v_cvt_pk_bf16_f32 v178, v231, v232
	v_cvt_pk_bf16_f32 v179, v233, v234
	ds_read_b64_tr_b16 v[230:231], v160 offset:0x2000
	ds_read_b64_tr_b16 v[232:233], v160 offset:0x2800
	v_permlane32_swap_b32_e32 v176, v178
	v_permlane32_swap_b32_e32 v177, v179
	ds_read_b64_tr_b16 v[222:223], v160 offset:0x400
	ds_read_b64_tr_b16 v[224:225], v160 offset:0xc00
	ds_read_b64_tr_b16 v[234:235], v160 offset:0x3000
	s_waitcnt lgkmcnt(5)
	v_mfma_f32_32x32x16_bf16 v[16:31], v[226:229], v[176:179], v[16:31]
	s_waitcnt lgkmcnt(3)
	v_mfma_f32_32x32x16_bf16 v[16:31], v[230:233], v[180:183], v[16:31]
	ds_read_b64_tr_b16 v[226:227], v160 offset:0x1200
	ds_read_b64_tr_b16 v[228:229], v160 offset:0x1a00
	s_waitcnt lgkmcnt(3)
	v_mfma_f32_32x32x16_bf16 v[32:47], v[222:225], v[172:175], v[32:47]
	ds_read_b64_tr_b16 v[230:231], v160 offset:0x2200
	ds_read_b64_tr_b16 v[232:233], v160 offset:0x2a00
	s_waitcnt lgkmcnt(4)
; DI int v_rd_base(int lane) { return ((lane & 3) << 3) | (((lane >> 2) & 3) << 6) | (((lane >> 4) & 1) << 5) | (((lane >> 5) & 1) << 8); }
; #define RBAR() do { asm volatile("s_waitcnt vmcnt(0) lgkmcnt(0)" ::: "memory"); __builtin_amdgcn_s_barrier(); asm volatile("" ::: "memory"); } while (0)
; DI void partialSM(f32x16& p0, f32x16& p1, float& m_reg, float& mn, float& alpha, const float SCALE) {
;   const float C = SCALE * 1.4426950408889634f;
;   float pmax = p0[0];
; #pragma unroll
;   for (int r = 1; r < 16; ++r) pmax = fmaxf(pmax, p0[r]);
; #pragma unroll
;   for (int r = 0; r < 16; ++r) pmax = fmaxf(pmax, p1[r]);
;   { auto rr = __builtin_amdgcn_permlane32_swap(__float_as_uint(pmax), __float_as_uint(pmax), false, false);
;     pmax = fmaxf(__uint_as_float(rr[0]), __uint_as_float(rr[1])); }
;   if (__builtin_expect(__all(pmax - m_reg <= THR / SCALE), 1)) { mn = m_reg; alpha = 1.f; }
;   else { mn = fmaxf(m_reg, pmax); alpha = __builtin_amdgcn_exp2f((m_reg - mn) * C); m_reg = mn; }
; template <int NPE, int LDQ, int LDK, int VOFF, int LDO> ...
;     ...
;   f32x16 pA0, pA1, pB0, pB1; float mnA, mnB, alA, alB; bf16x8 pa0, pa1, pa2, pa3; const int NT = seq / KVBLK;
;   const int vlane = v_rd_base(lane);
;   RBAR();
;   ISSUE(2 * KVBLK, s_next);
;   qkt_r<NPE>(pA0, pA1, s_prev + R_K, s_prev + R_P, qr, r32, hi); partialSM(pA0, pA1, m_reg, mnA, alA, SCALE);
	v_mfma_f32_32x32x16_bf16 v[16:31], v[234:237], v[218:221], v[16:31]
	ds_read_b64_tr_b16 v[222:223], v160 offset:0x600
	ds_read_b64_tr_b16 v[224:225], v160 offset:0xe00
	ds_read_b64_tr_b16 v[234:235], v160 offset:0x3400
	ds_read_b64_tr_b16 v[236:237], v160 offset:0x3c00
	s_waitcnt lgkmcnt(6)
	v_mfma_f32_32x32x16_bf16 v[48:63], v[226:229], v[176:179], v[48:63]
	s_waitcnt lgkmcnt(4)
	v_mfma_f32_32x32x16_bf16 v[48:63], v[230:233], v[180:183], v[48:63]
	ds_read_b64_tr_b16 v[226:227], v160 offset:0x1400
	ds_read_b64_tr_b16 v[228:229], v160 offset:0x1c00
	v_mfma_f32_32x32x16_bf16 v[48:63], v[238:241], v[218:221], v[48:63]
	ds_read_b64_tr_b16 v[230:231], v160 offset:0x2400
	ds_read_b64_tr_b16 v[232:233], v160 offset:0x2c00
	s_waitcnt lgkmcnt(6)
	v_mfma_f32_32x32x16_bf16 v[0:15], v[222:225], v[172:175], v[0:15]
	ds_read_b64_tr_b16 v[238:239], v160 offset:0x3600
	ds_read_b64_tr_b16 v[240:241], v160 offset:0x3e00
	s_waitcnt lgkmcnt(4)
	v_mfma_f32_32x32x16_bf16 v[32:47], v[226:229], v[176:179], v[32:47]
	s_waitcnt lgkmcnt(2)
	v_mfma_f32_32x32x16_bf16 v[32:47], v[230:233], v[180:183], v[32:47]
	ds_read_b64_tr_b16 v[226:227], v160 offset:0x1600
	ds_read_b64_tr_b16 v[228:229], v160 offset:0x1e00
	v_mfma_f32_32x32x16_bf16 v[32:47], v[234:237], v[218:221], v[32:47]
	ds_read_b64_tr_b16 v[230:231], v160 offset:0x2600
	ds_read_b64_tr_b16 v[232:233], v160 offset:0x2e00
	v_max_f32_e32 v160, v65, v65
	v_max_f32_e32 v160, v171, v160
	v_max3_f32 v160, v160, v66, v67
	v_max3_f32 v160, v160, v68, v69
	v_max3_f32 v160, v160, v70, v71
	v_max3_f32 v160, v160, v72, v73
	v_max3_f32 v160, v160, v74, v75
	v_max3_f32 v160, v160, v76, v77
	v_max3_f32 v160, v160, v78, v79
	v_max3_f32 v160, v160, v80, v81
	v_max3_f32 v160, v160, v82, v83
	v_max3_f32 v160, v160, v84, v85
	v_max3_f32 v160, v160, v86, v87
	v_max3_f32 v160, v160, v88, v89
	v_max3_f32 v160, v160, v90, v91
	v_max3_f32 v160, v160, v92, v93
	v_max3_f32 v160, v160, v94, v95
	v_mov_b32_e32 v171, v160
	s_waitcnt lgkmcnt(2)
	v_mfma_f32_32x32x16_bf16 v[0:15], v[226:229], v[176:179], v[0:15]
	s_waitcnt lgkmcnt(0)
	v_mfma_f32_32x32x16_bf16 v[0:15], v[230:233], v[180:183], v[0:15]
	v_permlane32_swap_b32_e32 v160, v171
	v_max_f32_e32 v171, v171, v171
	v_max_f32_e32 v160, v160, v160
	v_max_f32_e32 v160, v160, v171
	v_mfma_f32_32x32x16_bf16 v[0:15], v[238:241], v[218:221], v[0:15]
	v_max_f32_e32 v171, v170, v170
	v_sub_f32_e32 v172, v160, v170
	v_max_f32_e32 v171, v171, v160
	v_cmp_ge_f32_e32 vcc, s91, v172
	v_sub_f32_e32 v160, v170, v171
	v_mul_f32_e32 v160, 0x3dd53b94, v160
	s_cmp_eq_u64 vcc, exec
	v_exp_f32_e32 v160, v160
	s_cselect_b64 s[2:3], -1, 0
	v_cndmask_b32_e64 v160, v160, 1.0, s[2:3]
	s_cbranch_scc1 .LBB0_932
	v_pk_mul_f32 v[30:31], v[30:31], v[160:161] op_sel_hi:[1,0]
	v_pk_mul_f32 v[28:29], v[28:29], v[160:161] op_sel_hi:[1,0]
	v_pk_mul_f32 v[26:27], v[26:27], v[160:161] op_sel_hi:[1,0]
	v_pk_mul_f32 v[24:25], v[24:25], v[160:161] op_sel_hi:[1,0]
	v_pk_mul_f32 v[22:23], v[22:23], v[160:161] op_sel_hi:[1,0]
	v_pk_mul_f32 v[20:21], v[20:21], v[160:161] op_sel_hi:[1,0]
	v_pk_mul_f32 v[18:19], v[18:19], v[160:161] op_sel_hi:[1,0]
	v_pk_mul_f32 v[16:17], v[16:17], v[160:161] op_sel_hi:[1,0]
	v_pk_mul_f32 v[62:63], v[62:63], v[160:161] op_sel_hi:[1,0]
	v_pk_mul_f32 v[60:61], v[60:61], v[160:161] op_sel_hi:[1,0]
	v_pk_mul_f32 v[58:59], v[58:59], v[160:161] op_sel_hi:[1,0]
	v_pk_mul_f32 v[56:57], v[56:57], v[160:161] op_sel_hi:[1,0]
	v_pk_mul_f32 v[54:55], v[54:55], v[160:161] op_sel_hi:[1,0]
	v_pk_mul_f32 v[52:53], v[52:53], v[160:161] op_sel_hi:[1,0]
	v_pk_mul_f32 v[50:51], v[50:51], v[160:161] op_sel_hi:[1,0]
	v_pk_mul_f32 v[48:49], v[48:49], v[160:161] op_sel_hi:[1,0]
	v_pk_mul_f32 v[46:47], v[46:47], v[160:161] op_sel_hi:[1,0]
	v_pk_mul_f32 v[44:45], v[44:45], v[160:161] op_sel_hi:[1,0]
	v_pk_mul_f32 v[42:43], v[42:43], v[160:161] op_sel_hi:[1,0]
	v_pk_mul_f32 v[40:41], v[40:41], v[160:161] op_sel_hi:[1,0]
	v_pk_mul_f32 v[38:39], v[38:39], v[160:161] op_sel_hi:[1,0]
	v_pk_mul_f32 v[36:37], v[36:37], v[160:161] op_sel_hi:[1,0]
	v_pk_mul_f32 v[34:35], v[34:35], v[160:161] op_sel_hi:[1,0]
	v_pk_mul_f32 v[32:33], v[32:33], v[160:161] op_sel_hi:[1,0]
	v_pk_mul_f32 v[14:15], v[14:15], v[160:161] op_sel_hi:[1,0]
	v_pk_mul_f32 v[12:13], v[12:13], v[160:161] op_sel_hi:[1,0]
	v_pk_mul_f32 v[10:11], v[10:11], v[160:161] op_sel_hi:[1,0]
	v_pk_mul_f32 v[8:9], v[8:9], v[160:161] op_sel_hi:[1,0]
	v_pk_mul_f32 v[6:7], v[6:7], v[160:161] op_sel_hi:[1,0]
	v_pk_mul_f32 v[4:5], v[4:5], v[160:161] op_sel_hi:[1,0]
	v_pk_mul_f32 v[2:3], v[2:3], v[160:161] op_sel_hi:[1,0]
	v_pk_mul_f32 v[0:1], v[0:1], v[160:161] op_sel_hi:[1,0]
